# main GEMM K-loops: MFMA issue order changed to a snake over (m,n) so consecutive MFMAs share one operand
# speedup vs baseline: 1.0181x; 1.0052x over previous
.LBB0_255:
	s_ashr_i32 s15, s14, 31
	s_lshl_b64 s[20:21], s[14:15], 19
	s_add_u32 s42, s31, s20
	s_addc_u32 s43, s34, s21
	s_and_b64 s[20:21], s[4:5], exec
	s_cselect_b32 s15, s43, s53
	s_cselect_b32 s20, s42, s52
	s_ashr_i32 s13, s12, 31
	s_lshl_b64 s[50:51], s[12:13], 19
	s_add_u32 s50, s35, s50
	s_addc_u32 s51, s36, s51
	s_and_b64 s[58:59], s[4:5], exec
	s_cselect_b32 s13, s51, s57
	s_cselect_b32 s21, s50, s56
	s_add_u32 s52, s52, 0x40080
	s_addc_u32 s53, s53, 0
	s_add_u32 s73, s56, 0x100
	s_addc_u32 s75, s57, 0
	s_mov_b32 s82, -2
	s_add_u32 s0, s52, 0xfffc0080
	s_addc_u32 s56, s53, -1
	s_add_i32 s83, 0, 0x10000
	s_cmp_eq_u32 s82, 12
	s_cselect_b32 s59, s15, s56
	s_cselect_b32 s58, s20, s0
	s_cselect_b32 s57, s13, s75
	s_cselect_b32 s56, s21, s73
	s_add_i32 s0, 0, 0x14000
	v_add_u32_e32 v94, s83, v171
	v_add_u32_e32 v155, s0, v171
	ds_read_b128 v[74:77], v94
	ds_read_b128 v[78:81], v94 offset:1024
	ds_read_b128 v[90:93], v94 offset:2048
	ds_read_b128 v[94:97], v94 offset:3072
	ds_read_b128 v[180:183], v155
	ds_read_b128 v[184:187], v155 offset:1024
	ds_read_b128 v[188:191], v155 offset:2048
	ds_read_b128 v[192:195], v155 offset:3072
	v_lshl_add_u64 v[168:169], s[52:53], 0, v[164:165]
	s_add_i32 m0, s61, 0xc000
	ds_read_b128 v[196:199], v177
	ds_read_b128 v[200:203], v177 offset:1024
	ds_read_b128 v[204:207], v177 offset:2048
	ds_read_b128 v[208:211], v177 offset:3072
	ds_read_b128 v[212:215], v177 offset:4096
	ds_read_b128 v[216:219], v177 offset:5120
	ds_read_b128 v[230:233], v177 offset:6144
	ds_read_b128 v[238:241], v177 offset:7168
	global_load_lds_dwordx4 v[168:169], off
	v_lshl_add_u64 v[168:169], s[52:53], 0, v[166:167]
	s_add_i32 m0, s61, 0xe000
	s_nop 0
	global_load_lds_dwordx4 v[168:169], off
	s_waitcnt vmcnt(8)
	s_waitcnt lgkmcnt(0)
	s_barrier
	s_setprio 1
	s_waitcnt lgkmcnt(0)
	v_mfma_f32_16x16x32_bf16 v[142:145], v[74:77], v[196:199], 0
	v_mfma_f32_16x16x32_bf16 v[134:137], v[90:93], v[196:199], 0
	v_mfma_f32_16x16x32_bf16 v[118:121], v[90:93], v[204:207], 0
	v_mfma_f32_16x16x32_bf16 v[126:129], v[74:77], v[204:207], 0
	v_mfma_f32_16x16x32_bf16 v[110:113], v[74:77], v[212:215], 0
	v_mfma_f32_16x16x32_bf16 v[102:105], v[90:93], v[212:215], 0
	v_mfma_f32_16x16x32_bf16 v[70:73], v[90:93], v[230:233], 0
	v_mfma_f32_16x16x32_bf16 v[86:89], v[74:77], v[230:233], 0
	v_mfma_f32_16x16x32_bf16 v[142:145], v[78:81], v[200:203], v[142:145]
	v_mfma_f32_16x16x32_bf16 v[134:137], v[94:97], v[200:203], v[134:137]
	v_mfma_f32_16x16x32_bf16 v[118:121], v[94:97], v[208:211], v[118:121]
	v_mfma_f32_16x16x32_bf16 v[126:129], v[78:81], v[208:211], v[126:129]
	v_mfma_f32_16x16x32_bf16 v[110:113], v[78:81], v[216:219], v[110:113]
	v_mfma_f32_16x16x32_bf16 v[102:105], v[94:97], v[216:219], v[102:105]
	v_mfma_f32_16x16x32_bf16 v[70:73], v[94:97], v[238:241], v[70:73]
	v_mfma_f32_16x16x32_bf16 v[86:89], v[78:81], v[238:241], v[86:89]
	s_setprio 0
	s_setprio 1
	v_mfma_f32_16x16x32_bf16 v[138:141], v[180:183], v[196:199], 0
	v_mfma_f32_16x16x32_bf16 v[130:133], v[188:191], v[196:199], 0
	v_mfma_f32_16x16x32_bf16 v[114:117], v[188:191], v[204:207], 0
	v_mfma_f32_16x16x32_bf16 v[122:125], v[180:183], v[204:207], 0
	v_mfma_f32_16x16x32_bf16 v[106:109], v[180:183], v[212:215], 0
	v_mfma_f32_16x16x32_bf16 v[98:101], v[188:191], v[212:215], 0
	v_mfma_f32_16x16x32_bf16 v[66:69], v[188:191], v[230:233], 0
	v_mfma_f32_16x16x32_bf16 v[82:85], v[180:183], v[230:233], 0
	v_mfma_f32_16x16x32_bf16 v[138:141], v[184:187], v[200:203], v[138:141]
	v_mfma_f32_16x16x32_bf16 v[130:133], v[192:195], v[200:203], v[130:133]
	v_mfma_f32_16x16x32_bf16 v[114:117], v[192:195], v[208:211], v[114:117]
	v_mfma_f32_16x16x32_bf16 v[122:125], v[184:187], v[208:211], v[122:125]
	v_mfma_f32_16x16x32_bf16 v[106:109], v[184:187], v[216:219], v[106:109]
	v_mfma_f32_16x16x32_bf16 v[98:101], v[192:195], v[216:219], v[98:101]
	v_mfma_f32_16x16x32_bf16 v[66:69], v[192:195], v[238:241], v[66:69]
	v_mfma_f32_16x16x32_bf16 v[82:85], v[184:187], v[238:241], v[82:85]
	s_setprio 0
	s_barrier
	s_add_i32 s83, s83, s37
	v_lshl_add_u64 v[168:169], s[56:57], 0, v[150:151]
	s_mov_b32 m0, s83
	ds_read_b128 v[196:199], v177 offset:16384
	ds_read_b128 v[200:203], v177 offset:17408
	ds_read_b128 v[204:207], v177 offset:18432
	ds_read_b128 v[208:211], v177 offset:19456
	ds_read_b128 v[212:215], v177 offset:20480
	ds_read_b128 v[216:219], v177 offset:21504
	ds_read_b128 v[230:233], v177 offset:22528
	ds_read_b128 v[238:241], v177 offset:23552
	global_load_lds_dwordx4 v[168:169], off
	s_add_i32 m0, s83, 0x2000
	s_add_u32 s84, s56, 0x40000
	v_lshl_add_u64 v[242:243], s[56:57], 0, v[146:147]
	s_addc_u32 s85, s57, 0
	s_add_i32 s0, s0, s37
	global_load_lds_dwordx4 v[242:243], off
	v_lshl_add_u64 v[244:245], s[84:85], 0, v[150:151]
	s_mov_b32 m0, s0
	v_lshl_add_u64 v[246:247], s[58:59], 0, v[148:149]
	global_load_lds_dwordx4 v[244:245], off
	v_lshl_add_u64 v[244:245], s[84:85], 0, v[146:147]
	s_add_i32 m0, s0, 0x2000
	s_nop 0
	global_load_lds_dwordx4 v[244:245], off
	v_lshl_add_u64 v[244:245], s[58:59], 0, v[152:153]
	s_mov_b32 m0, s61
	s_nop 0
	global_load_lds_dwordx4 v[244:245], off
	s_mov_b32 m0, s64
	s_nop 0
	global_load_lds_dwordx4 v[246:247], off
	s_waitcnt vmcnt(8)
	s_waitcnt lgkmcnt(0)
	s_barrier
	s_setprio 1
	s_waitcnt lgkmcnt(0)
	v_mfma_f32_16x16x32_bf16 v[62:65], v[74:77], v[196:199], 0
	v_mfma_f32_16x16x32_bf16 v[54:57], v[90:93], v[196:199], 0
	v_mfma_f32_16x16x32_bf16 v[38:41], v[90:93], v[204:207], 0
	v_mfma_f32_16x16x32_bf16 v[46:49], v[74:77], v[204:207], 0
	v_mfma_f32_16x16x32_bf16 v[30:33], v[74:77], v[212:215], 0
	v_mfma_f32_16x16x32_bf16 v[22:25], v[90:93], v[212:215], 0
	v_mfma_f32_16x16x32_bf16 v[6:9], v[90:93], v[230:233], 0
	v_mfma_f32_16x16x32_bf16 v[14:17], v[74:77], v[230:233], 0
	v_mfma_f32_16x16x32_bf16 v[62:65], v[78:81], v[200:203], v[62:65]
	v_mfma_f32_16x16x32_bf16 v[54:57], v[94:97], v[200:203], v[54:57]
	v_mfma_f32_16x16x32_bf16 v[38:41], v[94:97], v[208:211], v[38:41]
	v_mfma_f32_16x16x32_bf16 v[46:49], v[78:81], v[208:211], v[46:49]
	v_mfma_f32_16x16x32_bf16 v[30:33], v[78:81], v[216:219], v[30:33]
	v_mfma_f32_16x16x32_bf16 v[22:25], v[94:97], v[216:219], v[22:25]
	v_mfma_f32_16x16x32_bf16 v[6:9], v[94:97], v[238:241], v[6:9]
	v_mfma_f32_16x16x32_bf16 v[14:17], v[78:81], v[238:241], v[14:17]
	s_setprio 0
	s_setprio 1
	v_mfma_f32_16x16x32_bf16 v[58:61], v[180:183], v[196:199], 0
	v_mfma_f32_16x16x32_bf16 v[50:53], v[188:191], v[196:199], 0
	v_mfma_f32_16x16x32_bf16 v[34:37], v[188:191], v[204:207], 0
	v_mfma_f32_16x16x32_bf16 v[42:45], v[180:183], v[204:207], 0
	v_mfma_f32_16x16x32_bf16 v[26:29], v[180:183], v[212:215], 0
	v_mfma_f32_16x16x32_bf16 v[18:21], v[188:191], v[212:215], 0
	v_mfma_f32_16x16x32_bf16 v[2:5], v[188:191], v[230:233], 0
	v_mfma_f32_16x16x32_bf16 v[10:13], v[180:183], v[230:233], 0
	v_mfma_f32_16x16x32_bf16 v[58:61], v[184:187], v[200:203], v[58:61]
	v_mfma_f32_16x16x32_bf16 v[50:53], v[192:195], v[200:203], v[50:53]
	v_mfma_f32_16x16x32_bf16 v[34:37], v[192:195], v[208:211], v[34:37]
	v_mfma_f32_16x16x32_bf16 v[42:45], v[184:187], v[208:211], v[42:45]
	v_mfma_f32_16x16x32_bf16 v[26:29], v[184:187], v[216:219], v[26:29]
	v_mfma_f32_16x16x32_bf16 v[18:21], v[192:195], v[216:219], v[18:21]
	v_mfma_f32_16x16x32_bf16 v[2:5], v[192:195], v[238:241], v[2:5]
	v_mfma_f32_16x16x32_bf16 v[10:13], v[184:187], v[238:241], v[10:13]
	s_setprio 0
	s_barrier
	s_add_i32 s0, 0, 0x18000
	s_add_i32 s83, 0, 0x1c000
	v_add_u32_e32 v94, s0, v171
	v_add_u32_e32 v155, s83, v171
	ds_read_b128 v[74:77], v94
	ds_read_b128 v[78:81], v94 offset:1024
	ds_read_b128 v[90:93], v94 offset:2048
	ds_read_b128 v[94:97], v94 offset:3072
	ds_read_b128 v[180:183], v155
	ds_read_b128 v[184:187], v155 offset:1024
	ds_read_b128 v[188:191], v155 offset:2048
	ds_read_b128 v[192:195], v155 offset:3072
	s_add_u32 s58, s58, 0x40000
	s_addc_u32 s59, s59, 0
	s_mov_b32 m0, s65
	v_lshl_add_u64 v[248:249], s[58:59], 0, v[152:153]
	ds_read_b128 v[196:199], v177 offset:32768
	ds_read_b128 v[200:203], v177 offset:33792
	ds_read_b128 v[204:207], v177 offset:34816
	ds_read_b128 v[208:211], v177 offset:35840
	ds_read_b128 v[212:215], v177 offset:36864
	ds_read_b128 v[216:219], v177 offset:37888
	ds_read_b128 v[230:233], v177 offset:38912
	ds_read_b128 v[238:241], v177 offset:39936
	global_load_lds_dwordx4 v[248:249], off
	v_lshl_add_u64 v[248:249], s[58:59], 0, v[148:149]
	s_mov_b32 m0, s66
	s_nop 0
	global_load_lds_dwordx4 v[248:249], off
	s_waitcnt vmcnt(8)
	s_waitcnt lgkmcnt(0)
	s_barrier
	s_setprio 1
	s_waitcnt lgkmcnt(0)
	v_mfma_f32_16x16x32_bf16 v[142:145], v[74:77], v[196:199], v[142:145]
	v_mfma_f32_16x16x32_bf16 v[134:137], v[90:93], v[196:199], v[134:137]
	v_mfma_f32_16x16x32_bf16 v[118:121], v[90:93], v[204:207], v[118:121]
	v_mfma_f32_16x16x32_bf16 v[126:129], v[74:77], v[204:207], v[126:129]
	v_mfma_f32_16x16x32_bf16 v[110:113], v[74:77], v[212:215], v[110:113]
	v_mfma_f32_16x16x32_bf16 v[102:105], v[90:93], v[212:215], v[102:105]
	v_mfma_f32_16x16x32_bf16 v[70:73], v[90:93], v[230:233], v[70:73]
	v_mfma_f32_16x16x32_bf16 v[86:89], v[74:77], v[230:233], v[86:89]
	v_mfma_f32_16x16x32_bf16 v[142:145], v[78:81], v[200:203], v[142:145]
	v_mfma_f32_16x16x32_bf16 v[134:137], v[94:97], v[200:203], v[134:137]
	v_mfma_f32_16x16x32_bf16 v[118:121], v[94:97], v[208:211], v[118:121]
	v_mfma_f32_16x16x32_bf16 v[126:129], v[78:81], v[208:211], v[126:129]
	v_mfma_f32_16x16x32_bf16 v[110:113], v[78:81], v[216:219], v[110:113]
	v_mfma_f32_16x16x32_bf16 v[102:105], v[94:97], v[216:219], v[102:105]
	v_mfma_f32_16x16x32_bf16 v[70:73], v[94:97], v[238:241], v[70:73]
	v_mfma_f32_16x16x32_bf16 v[86:89], v[78:81], v[238:241], v[86:89]
	s_setprio 0
	s_setprio 1
	v_mfma_f32_16x16x32_bf16 v[138:141], v[180:183], v[196:199], v[138:141]
	v_mfma_f32_16x16x32_bf16 v[130:133], v[188:191], v[196:199], v[130:133]
	v_mfma_f32_16x16x32_bf16 v[114:117], v[188:191], v[204:207], v[114:117]
	v_mfma_f32_16x16x32_bf16 v[122:125], v[180:183], v[204:207], v[122:125]
	v_mfma_f32_16x16x32_bf16 v[106:109], v[180:183], v[212:215], v[106:109]
	v_mfma_f32_16x16x32_bf16 v[98:101], v[188:191], v[212:215], v[98:101]
	v_mfma_f32_16x16x32_bf16 v[66:69], v[188:191], v[230:233], v[66:69]
	v_mfma_f32_16x16x32_bf16 v[82:85], v[180:183], v[230:233], v[82:85]
	v_mfma_f32_16x16x32_bf16 v[138:141], v[184:187], v[200:203], v[138:141]
	v_mfma_f32_16x16x32_bf16 v[130:133], v[192:195], v[200:203], v[130:133]
	v_mfma_f32_16x16x32_bf16 v[114:117], v[192:195], v[208:211], v[114:117]
	v_mfma_f32_16x16x32_bf16 v[122:125], v[184:187], v[208:211], v[122:125]
	v_mfma_f32_16x16x32_bf16 v[106:109], v[184:187], v[216:219], v[106:109]
	v_mfma_f32_16x16x32_bf16 v[98:101], v[192:195], v[216:219], v[98:101]
	v_mfma_f32_16x16x32_bf16 v[66:69], v[192:195], v[238:241], v[66:69]
	v_mfma_f32_16x16x32_bf16 v[82:85], v[184:187], v[238:241], v[82:85]
	s_setprio 0
	s_barrier
	s_add_i32 s0, s0, s37
	v_lshl_add_u64 v[168:169], v[168:169], 0, s[76:77]
	s_mov_b32 m0, s0
	ds_read_b128 v[196:199], v177 offset:49152
	ds_read_b128 v[200:203], v177 offset:50176
	ds_read_b128 v[204:207], v177 offset:51200
	ds_read_b128 v[208:211], v177 offset:52224
	ds_read_b128 v[212:215], v177 offset:53248
	ds_read_b128 v[216:219], v177 offset:54272
	ds_read_b128 v[230:233], v177 offset:55296
	ds_read_b128 v[238:241], v177 offset:56320
	global_load_lds_dwordx4 v[168:169], off
	s_add_i32 m0, s0, 0x2000
	s_add_u32 s56, s56, 0x40080
	v_lshl_add_u64 v[168:169], v[242:243], 0, s[76:77]
	s_addc_u32 s57, s57, 0
	s_add_i32 s0, s83, s37
	global_load_lds_dwordx4 v[168:169], off
	v_lshl_add_u64 v[168:169], s[56:57], 0, v[150:151]
	s_mov_b32 m0, s0
	s_nop 0
	global_load_lds_dwordx4 v[168:169], off
	v_lshl_add_u64 v[168:169], s[56:57], 0, v[146:147]
	s_add_i32 m0, s0, 0x2000
	s_nop 0
	global_load_lds_dwordx4 v[168:169], off
	v_lshl_add_u64 v[168:169], v[244:245], 0, s[76:77]
	s_mov_b32 m0, s67
	s_nop 0
	global_load_lds_dwordx4 v[168:169], off
	v_lshl_add_u64 v[168:169], v[246:247], 0, s[76:77]
	s_mov_b32 m0, s68
	s_nop 0
	global_load_lds_dwordx4 v[168:169], off
	s_waitcnt vmcnt(8)
	s_waitcnt lgkmcnt(0)
	s_barrier
	s_setprio 1
	s_waitcnt lgkmcnt(0)
	v_mfma_f32_16x16x32_bf16 v[62:65], v[74:77], v[196:199], v[62:65]
	v_mfma_f32_16x16x32_bf16 v[54:57], v[90:93], v[196:199], v[54:57]
	v_mfma_f32_16x16x32_bf16 v[38:41], v[90:93], v[204:207], v[38:41]
	v_mfma_f32_16x16x32_bf16 v[46:49], v[74:77], v[204:207], v[46:49]
	v_mfma_f32_16x16x32_bf16 v[30:33], v[74:77], v[212:215], v[30:33]
	v_mfma_f32_16x16x32_bf16 v[22:25], v[90:93], v[212:215], v[22:25]
	v_mfma_f32_16x16x32_bf16 v[6:9], v[90:93], v[230:233], v[6:9]
	v_mfma_f32_16x16x32_bf16 v[14:17], v[74:77], v[230:233], v[14:17]
	v_mfma_f32_16x16x32_bf16 v[62:65], v[78:81], v[200:203], v[62:65]
	v_mfma_f32_16x16x32_bf16 v[54:57], v[94:97], v[200:203], v[54:57]
	v_mfma_f32_16x16x32_bf16 v[38:41], v[94:97], v[208:211], v[38:41]
	v_mfma_f32_16x16x32_bf16 v[46:49], v[78:81], v[208:211], v[46:49]
	v_mfma_f32_16x16x32_bf16 v[30:33], v[78:81], v[216:219], v[30:33]
	v_mfma_f32_16x16x32_bf16 v[22:25], v[94:97], v[216:219], v[22:25]
	v_mfma_f32_16x16x32_bf16 v[6:9], v[94:97], v[238:241], v[6:9]
	v_mfma_f32_16x16x32_bf16 v[14:17], v[78:81], v[238:241], v[14:17]
	s_setprio 0
	s_setprio 1
	v_mfma_f32_16x16x32_bf16 v[58:61], v[180:183], v[196:199], v[58:61]
	v_mfma_f32_16x16x32_bf16 v[50:53], v[188:191], v[196:199], v[50:53]
	v_mfma_f32_16x16x32_bf16 v[34:37], v[188:191], v[204:207], v[34:37]
	v_mfma_f32_16x16x32_bf16 v[42:45], v[180:183], v[204:207], v[42:45]
	v_mfma_f32_16x16x32_bf16 v[26:29], v[180:183], v[212:215], v[26:29]
	v_mfma_f32_16x16x32_bf16 v[18:21], v[188:191], v[212:215], v[18:21]
	v_mfma_f32_16x16x32_bf16 v[2:5], v[188:191], v[230:233], v[2:5]
	v_mfma_f32_16x16x32_bf16 v[10:13], v[180:183], v[230:233], v[10:13]
	v_mfma_f32_16x16x32_bf16 v[58:61], v[184:187], v[200:203], v[58:61]
	v_mfma_f32_16x16x32_bf16 v[50:53], v[192:195], v[200:203], v[50:53]
	v_mfma_f32_16x16x32_bf16 v[34:37], v[192:195], v[208:211], v[34:37]
	v_mfma_f32_16x16x32_bf16 v[42:45], v[184:187], v[208:211], v[42:45]
	v_mfma_f32_16x16x32_bf16 v[26:29], v[184:187], v[216:219], v[26:29]
	v_mfma_f32_16x16x32_bf16 v[18:21], v[192:195], v[216:219], v[18:21]
	v_mfma_f32_16x16x32_bf16 v[2:5], v[192:195], v[238:241], v[2:5]
	v_mfma_f32_16x16x32_bf16 v[10:13], v[184:187], v[238:241], v[10:13]
	s_setprio 0
	s_barrier
	s_add_i32 s82, s82, 2
	s_add_u32 s52, s52, 0x100
	s_addc_u32 s53, s53, 0
	s_add_u32 s73, s73, 0x100
	s_addc_u32 s75, s75, 0
.LBB0_256:
	s_add_u32 s0, s52, 0xfffc0080
	s_addc_u32 s56, s53, -1
	s_add_i32 s83, 0, 0x10000
	s_cmp_eq_u32 s82, 12
	s_cselect_b32 s59, s15, s56
	s_cselect_b32 s58, s20, s0
	s_cselect_b32 s57, s13, s75
	s_cselect_b32 s56, s21, s73
	s_add_i32 s0, 0, 0x14000
	v_add_u32_e32 v94, s83, v171
	v_add_u32_e32 v155, s0, v171
	ds_read_b128 v[74:77], v94
	ds_read_b128 v[78:81], v94 offset:1024
	ds_read_b128 v[90:93], v94 offset:2048
	ds_read_b128 v[94:97], v94 offset:3072
	ds_read_b128 v[180:183], v155
	ds_read_b128 v[184:187], v155 offset:1024
	ds_read_b128 v[188:191], v155 offset:2048
	ds_read_b128 v[192:195], v155 offset:3072
	v_lshl_add_u64 v[168:169], s[52:53], 0, v[164:165]
	s_add_i32 m0, s61, 0xc000
	ds_read_b128 v[196:199], v177
	ds_read_b128 v[200:203], v177 offset:1024
	ds_read_b128 v[204:207], v177 offset:2048
	ds_read_b128 v[208:211], v177 offset:3072
	ds_read_b128 v[212:215], v177 offset:4096
	ds_read_b128 v[216:219], v177 offset:5120
	ds_read_b128 v[230:233], v177 offset:6144
	ds_read_b128 v[238:241], v177 offset:7168
	global_load_lds_dwordx4 v[168:169], off
	v_lshl_add_u64 v[168:169], s[52:53], 0, v[166:167]
	s_add_i32 m0, s61, 0xe000
	s_nop 0
	global_load_lds_dwordx4 v[168:169], off
	s_waitcnt vmcnt(8)
	s_waitcnt lgkmcnt(0)
	s_barrier
	s_setprio 1
	s_waitcnt lgkmcnt(0)
	v_mfma_f32_16x16x32_bf16 v[142:145], v[74:77], v[196:199], v[142:145]
	v_mfma_f32_16x16x32_bf16 v[134:137], v[90:93], v[196:199], v[134:137]
	v_mfma_f32_16x16x32_bf16 v[118:121], v[90:93], v[204:207], v[118:121]
	v_mfma_f32_16x16x32_bf16 v[126:129], v[74:77], v[204:207], v[126:129]
	v_mfma_f32_16x16x32_bf16 v[110:113], v[74:77], v[212:215], v[110:113]
	v_mfma_f32_16x16x32_bf16 v[102:105], v[90:93], v[212:215], v[102:105]
	v_mfma_f32_16x16x32_bf16 v[70:73], v[90:93], v[230:233], v[70:73]
	v_mfma_f32_16x16x32_bf16 v[86:89], v[74:77], v[230:233], v[86:89]
	v_mfma_f32_16x16x32_bf16 v[142:145], v[78:81], v[200:203], v[142:145]
	v_mfma_f32_16x16x32_bf16 v[134:137], v[94:97], v[200:203], v[134:137]
	v_mfma_f32_16x16x32_bf16 v[118:121], v[94:97], v[208:211], v[118:121]
	v_mfma_f32_16x16x32_bf16 v[126:129], v[78:81], v[208:211], v[126:129]
	v_mfma_f32_16x16x32_bf16 v[110:113], v[78:81], v[216:219], v[110:113]
	v_mfma_f32_16x16x32_bf16 v[102:105], v[94:97], v[216:219], v[102:105]
	v_mfma_f32_16x16x32_bf16 v[70:73], v[94:97], v[238:241], v[70:73]
	v_mfma_f32_16x16x32_bf16 v[86:89], v[78:81], v[238:241], v[86:89]
	s_setprio 0
	s_setprio 1
	v_mfma_f32_16x16x32_bf16 v[138:141], v[180:183], v[196:199], v[138:141]
	v_mfma_f32_16x16x32_bf16 v[130:133], v[188:191], v[196:199], v[130:133]
	v_mfma_f32_16x16x32_bf16 v[114:117], v[188:191], v[204:207], v[114:117]
	v_mfma_f32_16x16x32_bf16 v[122:125], v[180:183], v[204:207], v[122:125]
	v_mfma_f32_16x16x32_bf16 v[106:109], v[180:183], v[212:215], v[106:109]
	v_mfma_f32_16x16x32_bf16 v[98:101], v[188:191], v[212:215], v[98:101]
	v_mfma_f32_16x16x32_bf16 v[66:69], v[188:191], v[230:233], v[66:69]
	v_mfma_f32_16x16x32_bf16 v[82:85], v[180:183], v[230:233], v[82:85]
	v_mfma_f32_16x16x32_bf16 v[138:141], v[184:187], v[200:203], v[138:141]
	v_mfma_f32_16x16x32_bf16 v[130:133], v[192:195], v[200:203], v[130:133]
	v_mfma_f32_16x16x32_bf16 v[114:117], v[192:195], v[208:211], v[114:117]
	v_mfma_f32_16x16x32_bf16 v[122:125], v[184:187], v[208:211], v[122:125]
	v_mfma_f32_16x16x32_bf16 v[106:109], v[184:187], v[216:219], v[106:109]
	v_mfma_f32_16x16x32_bf16 v[98:101], v[192:195], v[216:219], v[98:101]
	v_mfma_f32_16x16x32_bf16 v[66:69], v[192:195], v[238:241], v[66:69]
	v_mfma_f32_16x16x32_bf16 v[82:85], v[184:187], v[238:241], v[82:85]
	s_setprio 0
	s_barrier
	s_add_i32 s83, s83, s37
	v_lshl_add_u64 v[168:169], s[56:57], 0, v[150:151]
	s_mov_b32 m0, s83
	ds_read_b128 v[196:199], v177 offset:16384
	ds_read_b128 v[200:203], v177 offset:17408
	ds_read_b128 v[204:207], v177 offset:18432
	ds_read_b128 v[208:211], v177 offset:19456
	ds_read_b128 v[212:215], v177 offset:20480
	ds_read_b128 v[216:219], v177 offset:21504
	ds_read_b128 v[230:233], v177 offset:22528
	ds_read_b128 v[238:241], v177 offset:23552
	global_load_lds_dwordx4 v[168:169], off
	s_add_i32 m0, s83, 0x2000
	s_add_u32 s84, s56, 0x40000
	v_lshl_add_u64 v[242:243], s[56:57], 0, v[146:147]
	s_addc_u32 s85, s57, 0
	s_add_i32 s0, s0, s37
	global_load_lds_dwordx4 v[242:243], off
	v_lshl_add_u64 v[244:245], s[84:85], 0, v[150:151]
	s_mov_b32 m0, s0
	v_lshl_add_u64 v[246:247], s[58:59], 0, v[148:149]
	global_load_lds_dwordx4 v[244:245], off
	v_lshl_add_u64 v[244:245], s[84:85], 0, v[146:147]
	s_add_i32 m0, s0, 0x2000
	s_nop 0
	global_load_lds_dwordx4 v[244:245], off
	v_lshl_add_u64 v[244:245], s[58:59], 0, v[152:153]
	s_mov_b32 m0, s61
	s_nop 0
	global_load_lds_dwordx4 v[244:245], off
	s_mov_b32 m0, s64
	s_nop 0
	global_load_lds_dwordx4 v[246:247], off
	s_waitcnt vmcnt(8)
	s_waitcnt lgkmcnt(0)
	s_barrier
	s_setprio 1
	s_waitcnt lgkmcnt(0)
	v_mfma_f32_16x16x32_bf16 v[62:65], v[74:77], v[196:199], v[62:65]
	v_mfma_f32_16x16x32_bf16 v[54:57], v[90:93], v[196:199], v[54:57]
	v_mfma_f32_16x16x32_bf16 v[38:41], v[90:93], v[204:207], v[38:41]
	v_mfma_f32_16x16x32_bf16 v[46:49], v[74:77], v[204:207], v[46:49]
	v_mfma_f32_16x16x32_bf16 v[30:33], v[74:77], v[212:215], v[30:33]
	v_mfma_f32_16x16x32_bf16 v[22:25], v[90:93], v[212:215], v[22:25]
	v_mfma_f32_16x16x32_bf16 v[6:9], v[90:93], v[230:233], v[6:9]
	v_mfma_f32_16x16x32_bf16 v[14:17], v[74:77], v[230:233], v[14:17]
	v_mfma_f32_16x16x32_bf16 v[62:65], v[78:81], v[200:203], v[62:65]
	v_mfma_f32_16x16x32_bf16 v[54:57], v[94:97], v[200:203], v[54:57]
	v_mfma_f32_16x16x32_bf16 v[38:41], v[94:97], v[208:211], v[38:41]
	v_mfma_f32_16x16x32_bf16 v[46:49], v[78:81], v[208:211], v[46:49]
	v_mfma_f32_16x16x32_bf16 v[30:33], v[78:81], v[216:219], v[30:33]
	v_mfma_f32_16x16x32_bf16 v[22:25], v[94:97], v[216:219], v[22:25]
	v_mfma_f32_16x16x32_bf16 v[6:9], v[94:97], v[238:241], v[6:9]
	v_mfma_f32_16x16x32_bf16 v[14:17], v[78:81], v[238:241], v[14:17]
	s_setprio 0
	s_setprio 1
	v_mfma_f32_16x16x32_bf16 v[58:61], v[180:183], v[196:199], v[58:61]
	v_mfma_f32_16x16x32_bf16 v[50:53], v[188:191], v[196:199], v[50:53]
	v_mfma_f32_16x16x32_bf16 v[34:37], v[188:191], v[204:207], v[34:37]
	v_mfma_f32_16x16x32_bf16 v[42:45], v[180:183], v[204:207], v[42:45]
	v_mfma_f32_16x16x32_bf16 v[26:29], v[180:183], v[212:215], v[26:29]
	v_mfma_f32_16x16x32_bf16 v[18:21], v[188:191], v[212:215], v[18:21]
	v_mfma_f32_16x16x32_bf16 v[2:5], v[188:191], v[230:233], v[2:5]
	v_mfma_f32_16x16x32_bf16 v[10:13], v[180:183], v[230:233], v[10:13]
	v_mfma_f32_16x16x32_bf16 v[58:61], v[184:187], v[200:203], v[58:61]
	v_mfma_f32_16x16x32_bf16 v[50:53], v[192:195], v[200:203], v[50:53]
	v_mfma_f32_16x16x32_bf16 v[34:37], v[192:195], v[208:211], v[34:37]
	v_mfma_f32_16x16x32_bf16 v[42:45], v[184:187], v[208:211], v[42:45]
	v_mfma_f32_16x16x32_bf16 v[26:29], v[184:187], v[216:219], v[26:29]
	v_mfma_f32_16x16x32_bf16 v[18:21], v[192:195], v[216:219], v[18:21]
	v_mfma_f32_16x16x32_bf16 v[2:5], v[192:195], v[238:241], v[2:5]
	v_mfma_f32_16x16x32_bf16 v[10:13], v[184:187], v[238:241], v[10:13]
	s_setprio 0
	s_barrier
	s_add_i32 s0, 0, 0x18000
	s_add_i32 s83, 0, 0x1c000
	v_add_u32_e32 v94, s0, v171
	v_add_u32_e32 v155, s83, v171
	ds_read_b128 v[74:77], v94
	ds_read_b128 v[78:81], v94 offset:1024
	ds_read_b128 v[90:93], v94 offset:2048
	ds_read_b128 v[94:97], v94 offset:3072
	ds_read_b128 v[180:183], v155
	ds_read_b128 v[184:187], v155 offset:1024
	ds_read_b128 v[188:191], v155 offset:2048
	ds_read_b128 v[192:195], v155 offset:3072
	s_add_u32 s58, s58, 0x40000
	s_addc_u32 s59, s59, 0
	s_mov_b32 m0, s65
	v_lshl_add_u64 v[248:249], s[58:59], 0, v[152:153]
	ds_read_b128 v[196:199], v177 offset:32768
	ds_read_b128 v[200:203], v177 offset:33792
	ds_read_b128 v[204:207], v177 offset:34816
	ds_read_b128 v[208:211], v177 offset:35840
	ds_read_b128 v[212:215], v177 offset:36864
	ds_read_b128 v[216:219], v177 offset:37888
	ds_read_b128 v[230:233], v177 offset:38912
	ds_read_b128 v[238:241], v177 offset:39936
	global_load_lds_dwordx4 v[248:249], off
	v_lshl_add_u64 v[248:249], s[58:59], 0, v[148:149]
	s_mov_b32 m0, s66
	s_nop 0
	global_load_lds_dwordx4 v[248:249], off
	s_waitcnt vmcnt(8)
	s_waitcnt lgkmcnt(0)
	s_barrier
	s_setprio 1
	s_waitcnt lgkmcnt(0)
	v_mfma_f32_16x16x32_bf16 v[142:145], v[74:77], v[196:199], v[142:145]
	v_mfma_f32_16x16x32_bf16 v[134:137], v[90:93], v[196:199], v[134:137]
	v_mfma_f32_16x16x32_bf16 v[118:121], v[90:93], v[204:207], v[118:121]
	v_mfma_f32_16x16x32_bf16 v[126:129], v[74:77], v[204:207], v[126:129]
	v_mfma_f32_16x16x32_bf16 v[110:113], v[74:77], v[212:215], v[110:113]
	v_mfma_f32_16x16x32_bf16 v[102:105], v[90:93], v[212:215], v[102:105]
	v_mfma_f32_16x16x32_bf16 v[70:73], v[90:93], v[230:233], v[70:73]
	v_mfma_f32_16x16x32_bf16 v[86:89], v[74:77], v[230:233], v[86:89]
	v_mfma_f32_16x16x32_bf16 v[142:145], v[78:81], v[200:203], v[142:145]
	v_mfma_f32_16x16x32_bf16 v[134:137], v[94:97], v[200:203], v[134:137]
	v_mfma_f32_16x16x32_bf16 v[118:121], v[94:97], v[208:211], v[118:121]
	v_mfma_f32_16x16x32_bf16 v[126:129], v[78:81], v[208:211], v[126:129]
	v_mfma_f32_16x16x32_bf16 v[110:113], v[78:81], v[216:219], v[110:113]
	v_mfma_f32_16x16x32_bf16 v[102:105], v[94:97], v[216:219], v[102:105]
	v_mfma_f32_16x16x32_bf16 v[70:73], v[94:97], v[238:241], v[70:73]
	v_mfma_f32_16x16x32_bf16 v[86:89], v[78:81], v[238:241], v[86:89]
	s_setprio 0
	s_setprio 1
	v_mfma_f32_16x16x32_bf16 v[138:141], v[180:183], v[196:199], v[138:141]
	v_mfma_f32_16x16x32_bf16 v[130:133], v[188:191], v[196:199], v[130:133]
	v_mfma_f32_16x16x32_bf16 v[114:117], v[188:191], v[204:207], v[114:117]
	v_mfma_f32_16x16x32_bf16 v[122:125], v[180:183], v[204:207], v[122:125]
	v_mfma_f32_16x16x32_bf16 v[106:109], v[180:183], v[212:215], v[106:109]
	v_mfma_f32_16x16x32_bf16 v[98:101], v[188:191], v[212:215], v[98:101]
	v_mfma_f32_16x16x32_bf16 v[66:69], v[188:191], v[230:233], v[66:69]
	v_mfma_f32_16x16x32_bf16 v[82:85], v[180:183], v[230:233], v[82:85]
	v_mfma_f32_16x16x32_bf16 v[138:141], v[184:187], v[200:203], v[138:141]
	v_mfma_f32_16x16x32_bf16 v[130:133], v[192:195], v[200:203], v[130:133]
	v_mfma_f32_16x16x32_bf16 v[114:117], v[192:195], v[208:211], v[114:117]
	v_mfma_f32_16x16x32_bf16 v[122:125], v[184:187], v[208:211], v[122:125]
	v_mfma_f32_16x16x32_bf16 v[106:109], v[184:187], v[216:219], v[106:109]
	v_mfma_f32_16x16x32_bf16 v[98:101], v[192:195], v[216:219], v[98:101]
	v_mfma_f32_16x16x32_bf16 v[66:69], v[192:195], v[238:241], v[66:69]
	v_mfma_f32_16x16x32_bf16 v[82:85], v[184:187], v[238:241], v[82:85]
	s_setprio 0
	s_barrier
	s_add_i32 s0, s0, s37
	v_lshl_add_u64 v[168:169], v[168:169], 0, s[76:77]
	s_mov_b32 m0, s0
	ds_read_b128 v[196:199], v177 offset:49152
	ds_read_b128 v[200:203], v177 offset:50176
	ds_read_b128 v[204:207], v177 offset:51200
	ds_read_b128 v[208:211], v177 offset:52224
	ds_read_b128 v[212:215], v177 offset:53248
	ds_read_b128 v[216:219], v177 offset:54272
	ds_read_b128 v[230:233], v177 offset:55296
	ds_read_b128 v[238:241], v177 offset:56320
	global_load_lds_dwordx4 v[168:169], off
	s_add_i32 m0, s0, 0x2000
	s_add_u32 s56, s56, 0x40080
	v_lshl_add_u64 v[168:169], v[242:243], 0, s[76:77]
	s_addc_u32 s57, s57, 0
	s_add_i32 s0, s83, s37
	global_load_lds_dwordx4 v[168:169], off
	v_lshl_add_u64 v[168:169], s[56:57], 0, v[150:151]
	s_mov_b32 m0, s0
	s_nop 0
	global_load_lds_dwordx4 v[168:169], off
	v_lshl_add_u64 v[168:169], s[56:57], 0, v[146:147]
	s_add_i32 m0, s0, 0x2000
	s_nop 0
	global_load_lds_dwordx4 v[168:169], off
	v_lshl_add_u64 v[168:169], v[244:245], 0, s[76:77]
	s_mov_b32 m0, s67
	s_nop 0
	global_load_lds_dwordx4 v[168:169], off
	v_lshl_add_u64 v[168:169], v[246:247], 0, s[76:77]
	s_mov_b32 m0, s68
	s_nop 0
	global_load_lds_dwordx4 v[168:169], off
	s_waitcnt vmcnt(8)
	s_waitcnt lgkmcnt(0)
	s_barrier
	s_setprio 1
	s_waitcnt lgkmcnt(0)
	v_mfma_f32_16x16x32_bf16 v[62:65], v[74:77], v[196:199], v[62:65]
	v_mfma_f32_16x16x32_bf16 v[54:57], v[90:93], v[196:199], v[54:57]
	v_mfma_f32_16x16x32_bf16 v[38:41], v[90:93], v[204:207], v[38:41]
	v_mfma_f32_16x16x32_bf16 v[46:49], v[74:77], v[204:207], v[46:49]
	v_mfma_f32_16x16x32_bf16 v[30:33], v[74:77], v[212:215], v[30:33]
	v_mfma_f32_16x16x32_bf16 v[22:25], v[90:93], v[212:215], v[22:25]
	v_mfma_f32_16x16x32_bf16 v[6:9], v[90:93], v[230:233], v[6:9]
	v_mfma_f32_16x16x32_bf16 v[14:17], v[74:77], v[230:233], v[14:17]
	v_mfma_f32_16x16x32_bf16 v[62:65], v[78:81], v[200:203], v[62:65]
	v_mfma_f32_16x16x32_bf16 v[54:57], v[94:97], v[200:203], v[54:57]
	v_mfma_f32_16x16x32_bf16 v[38:41], v[94:97], v[208:211], v[38:41]
	v_mfma_f32_16x16x32_bf16 v[46:49], v[78:81], v[208:211], v[46:49]
	v_mfma_f32_16x16x32_bf16 v[30:33], v[78:81], v[216:219], v[30:33]
	v_mfma_f32_16x16x32_bf16 v[22:25], v[94:97], v[216:219], v[22:25]
	v_mfma_f32_16x16x32_bf16 v[6:9], v[94:97], v[238:241], v[6:9]
	v_mfma_f32_16x16x32_bf16 v[14:17], v[78:81], v[238:241], v[14:17]
	s_setprio 0
	s_setprio 1
	v_mfma_f32_16x16x32_bf16 v[58:61], v[180:183], v[196:199], v[58:61]
	v_mfma_f32_16x16x32_bf16 v[50:53], v[188:191], v[196:199], v[50:53]
	v_mfma_f32_16x16x32_bf16 v[34:37], v[188:191], v[204:207], v[34:37]
	v_mfma_f32_16x16x32_bf16 v[42:45], v[180:183], v[204:207], v[42:45]
	v_mfma_f32_16x16x32_bf16 v[26:29], v[180:183], v[212:215], v[26:29]
	v_mfma_f32_16x16x32_bf16 v[18:21], v[188:191], v[212:215], v[18:21]
	v_mfma_f32_16x16x32_bf16 v[2:5], v[188:191], v[230:233], v[2:5]
	v_mfma_f32_16x16x32_bf16 v[10:13], v[180:183], v[230:233], v[10:13]
	v_mfma_f32_16x16x32_bf16 v[58:61], v[184:187], v[200:203], v[58:61]
	v_mfma_f32_16x16x32_bf16 v[50:53], v[192:195], v[200:203], v[50:53]
	v_mfma_f32_16x16x32_bf16 v[34:37], v[192:195], v[208:211], v[34:37]
	v_mfma_f32_16x16x32_bf16 v[42:45], v[184:187], v[208:211], v[42:45]
	v_mfma_f32_16x16x32_bf16 v[26:29], v[184:187], v[216:219], v[26:29]
	v_mfma_f32_16x16x32_bf16 v[18:21], v[192:195], v[216:219], v[18:21]
	v_mfma_f32_16x16x32_bf16 v[2:5], v[192:195], v[238:241], v[2:5]
	v_mfma_f32_16x16x32_bf16 v[10:13], v[184:187], v[238:241], v[10:13]
	s_setprio 0
	s_barrier
	s_add_i32 s82, s82, 2
	s_add_u32 s52, s52, 0x100
	s_addc_u32 s53, s53, 0
	s_add_u32 s73, s73, 0x100
	s_addc_u32 s75, s75, 0
	s_cmp_gt_u32 s82, 13
	s_cbranch_scc0 .LBB0_256
	s_and_b64 vcc, exec, s[10:11]
	s_cbranch_vccz .LBB0_259
	s_barrier

.LBB0_282:
	s_ashr_i32 s59, s58, 31
	s_lshl_b64 s[20:21], s[58:59], 19
	s_add_u32 s64, s26, s20
	s_addc_u32 s65, s27, s21
	s_and_b64 s[20:21], s[8:9], exec
	s_cselect_b32 s20, s65, s5
	s_cselect_b32 s21, s64, s4
	s_ashr_i32 s57, s56, 31
	s_lshl_b64 s[36:37], s[56:57], 19
	s_add_u32 s66, s35, s36
	s_addc_u32 s67, s40, s37
	s_and_b64 s[36:37], s[8:9], exec
	s_cselect_b32 s36, s67, s7
	s_cselect_b32 s37, s66, s6
	s_add_u32 s4, s4, 0x40080
	s_addc_u32 s5, s5, 0
	s_add_u32 s46, s6, 0x100
	s_addc_u32 s57, s7, 0
	s_mov_b32 s59, -2
	s_add_u32 s6, s4, 0xfffc0080
	s_addc_u32 s7, s5, -1
	s_add_i32 s82, 0, 0x10000
	s_cmp_eq_u32 s59, 12
	s_cselect_b32 s69, s20, s7
	s_cselect_b32 s68, s21, s6
	s_cselect_b32 s7, s36, s57
	s_cselect_b32 s6, s37, s46
	s_add_i32 s84, 0, 0x14000
	v_add_u32_e32 v142, s82, v202
	v_add_u32_e32 v158, s84, v202
	ds_read_b128 v[130:133], v142
	ds_read_b128 v[134:137], v142 offset:1024
	ds_read_b128 v[138:141], v142 offset:2048
	ds_read_b128 v[142:145], v142 offset:3072
	ds_read_b128 v[146:149], v158
	ds_read_b128 v[150:153], v158 offset:1024
	ds_read_b128 v[154:157], v158 offset:2048
	ds_read_b128 v[158:161], v158 offset:3072
	v_lshl_add_u64 v[218:219], s[4:5], 0, v[182:183]
	s_add_i32 m0, s87, 0xc000
	ds_read_b128 v[186:189], v204
	ds_read_b128 v[190:193], v204 offset:1024
	ds_read_b128 v[194:197], v204 offset:2048
	ds_read_b128 v[198:201], v204 offset:3072
	ds_read_b128 v[206:209], v204 offset:4096
	ds_read_b128 v[210:213], v204 offset:5120
	ds_read_b128 v[214:217], v204 offset:6144
	ds_read_b128 v[238:241], v204 offset:7168
	global_load_lds_dwordx4 v[218:219], off
	v_lshl_add_u64 v[218:219], s[4:5], 0, v[184:185]
	s_add_i32 m0, s87, 0xe000
	s_nop 0
	global_load_lds_dwordx4 v[218:219], off
	s_waitcnt vmcnt(8)
	s_waitcnt lgkmcnt(0)
	s_barrier
	s_setprio 1
	s_waitcnt lgkmcnt(0)
	v_mfma_f32_16x16x32_bf16 v[2:5], v[130:133], v[186:189], 0
	v_mfma_f32_16x16x32_bf16 v[6:9], v[138:141], v[186:189], 0
	v_mfma_f32_16x16x32_bf16 v[26:29], v[138:141], v[194:197], 0
	v_mfma_f32_16x16x32_bf16 v[30:33], v[130:133], v[194:197], 0
	v_mfma_f32_16x16x32_bf16 v[34:37], v[130:133], v[206:209], 0
	v_mfma_f32_16x16x32_bf16 v[42:45], v[138:141], v[206:209], 0
	v_mfma_f32_16x16x32_bf16 v[58:61], v[138:141], v[214:217], 0
	v_mfma_f32_16x16x32_bf16 v[62:65], v[130:133], v[214:217], 0
	v_mfma_f32_16x16x32_bf16 v[2:5], v[134:137], v[190:193], v[2:5]
	v_mfma_f32_16x16x32_bf16 v[6:9], v[142:145], v[190:193], v[6:9]
	v_mfma_f32_16x16x32_bf16 v[26:29], v[142:145], v[198:201], v[26:29]
	v_mfma_f32_16x16x32_bf16 v[30:33], v[134:137], v[198:201], v[30:33]
	v_mfma_f32_16x16x32_bf16 v[34:37], v[134:137], v[210:213], v[34:37]
	v_mfma_f32_16x16x32_bf16 v[42:45], v[142:145], v[210:213], v[42:45]
	v_mfma_f32_16x16x32_bf16 v[58:61], v[142:145], v[238:241], v[58:61]
	v_mfma_f32_16x16x32_bf16 v[62:65], v[134:137], v[238:241], v[62:65]
	s_setprio 0
	s_setprio 1
	v_mfma_f32_16x16x32_bf16 v[14:17], v[146:149], v[186:189], 0
	v_mfma_f32_16x16x32_bf16 v[10:13], v[154:157], v[186:189], 0
	v_mfma_f32_16x16x32_bf16 v[18:21], v[154:157], v[194:197], 0
	v_mfma_f32_16x16x32_bf16 v[22:25], v[146:149], v[194:197], 0
	v_mfma_f32_16x16x32_bf16 v[46:49], v[146:149], v[206:209], 0
	v_mfma_f32_16x16x32_bf16 v[38:41], v[154:157], v[206:209], 0
	v_mfma_f32_16x16x32_bf16 v[50:53], v[154:157], v[214:217], 0
	v_mfma_f32_16x16x32_bf16 v[54:57], v[146:149], v[214:217], 0
	v_mfma_f32_16x16x32_bf16 v[14:17], v[150:153], v[190:193], v[14:17]
	v_mfma_f32_16x16x32_bf16 v[10:13], v[158:161], v[190:193], v[10:13]
	v_mfma_f32_16x16x32_bf16 v[18:21], v[158:161], v[198:201], v[18:21]
	v_mfma_f32_16x16x32_bf16 v[22:25], v[150:153], v[198:201], v[22:25]
	v_mfma_f32_16x16x32_bf16 v[46:49], v[150:153], v[210:213], v[46:49]
	v_mfma_f32_16x16x32_bf16 v[38:41], v[158:161], v[210:213], v[38:41]
	v_mfma_f32_16x16x32_bf16 v[50:53], v[158:161], v[238:241], v[50:53]
	v_mfma_f32_16x16x32_bf16 v[54:57], v[150:153], v[238:241], v[54:57]
	s_setprio 0
	s_barrier
	s_add_i32 s82, s82, s41
	v_lshl_add_u64 v[218:219], s[6:7], 0, v[164:165]
	s_mov_b32 m0, s82
	ds_read_b128 v[186:189], v204 offset:16384
	ds_read_b128 v[190:193], v204 offset:17408
	ds_read_b128 v[194:197], v204 offset:18432
	ds_read_b128 v[198:201], v204 offset:19456
	ds_read_b128 v[206:209], v204 offset:20480
	ds_read_b128 v[210:213], v204 offset:21504
	ds_read_b128 v[214:217], v204 offset:22528
	ds_read_b128 v[238:241], v204 offset:23552
	global_load_lds_dwordx4 v[218:219], off
	s_add_i32 m0, s82, 0x2000
	s_add_u32 s82, s6, 0x40000
	v_lshl_add_u64 v[230:231], s[6:7], 0, v[162:163]
	s_addc_u32 s83, s7, 0
	s_add_i32 s84, s84, s41
	global_load_lds_dwordx4 v[230:231], off
	v_lshl_add_u64 v[232:233], s[82:83], 0, v[164:165]
	s_mov_b32 m0, s84
	v_lshl_add_u64 v[242:243], s[68:69], 0, v[162:163]
	global_load_lds_dwordx4 v[232:233], off
	v_lshl_add_u64 v[232:233], s[82:83], 0, v[162:163]
	s_add_i32 m0, s84, 0x2000
	s_nop 0
	global_load_lds_dwordx4 v[232:233], off
	v_lshl_add_u64 v[232:233], s[68:69], 0, v[164:165]
	s_mov_b32 m0, s87
	s_nop 0
	global_load_lds_dwordx4 v[232:233], off
	s_mov_b32 m0, s75
	s_nop 0
	global_load_lds_dwordx4 v[242:243], off
	s_waitcnt vmcnt(8)
	s_waitcnt lgkmcnt(0)
	s_barrier
	s_setprio 1
	s_waitcnt lgkmcnt(0)
	v_mfma_f32_16x16x32_bf16 v[74:77], v[130:133], v[186:189], 0
	v_mfma_f32_16x16x32_bf16 v[70:73], v[138:141], v[186:189], 0
	v_mfma_f32_16x16x32_bf16 v[90:93], v[138:141], v[194:197], 0
	v_mfma_f32_16x16x32_bf16 v[94:97], v[130:133], v[194:197], 0
	v_mfma_f32_16x16x32_bf16 v[106:109], v[130:133], v[206:209], 0
	v_mfma_f32_16x16x32_bf16 v[102:105], v[138:141], v[206:209], 0
	v_mfma_f32_16x16x32_bf16 v[114:117], v[138:141], v[214:217], 0
	v_mfma_f32_16x16x32_bf16 v[118:121], v[130:133], v[214:217], 0
	v_mfma_f32_16x16x32_bf16 v[74:77], v[134:137], v[190:193], v[74:77]
	v_mfma_f32_16x16x32_bf16 v[70:73], v[142:145], v[190:193], v[70:73]
	v_mfma_f32_16x16x32_bf16 v[90:93], v[142:145], v[198:201], v[90:93]
	v_mfma_f32_16x16x32_bf16 v[94:97], v[134:137], v[198:201], v[94:97]
	v_mfma_f32_16x16x32_bf16 v[106:109], v[134:137], v[210:213], v[106:109]
	v_mfma_f32_16x16x32_bf16 v[102:105], v[142:145], v[210:213], v[102:105]
	v_mfma_f32_16x16x32_bf16 v[114:117], v[142:145], v[238:241], v[114:117]
	v_mfma_f32_16x16x32_bf16 v[118:121], v[134:137], v[238:241], v[118:121]
	s_setprio 0
	s_setprio 1
	v_mfma_f32_16x16x32_bf16 v[78:81], v[146:149], v[186:189], 0
	v_mfma_f32_16x16x32_bf16 v[66:69], v[154:157], v[186:189], 0
	v_mfma_f32_16x16x32_bf16 v[82:85], v[154:157], v[194:197], 0
	v_mfma_f32_16x16x32_bf16 v[86:89], v[146:149], v[194:197], 0
	v_mfma_f32_16x16x32_bf16 v[110:113], v[146:149], v[206:209], 0
	v_mfma_f32_16x16x32_bf16 v[98:101], v[154:157], v[206:209], 0
	v_mfma_f32_16x16x32_bf16 v[126:129], v[154:157], v[214:217], 0
	v_mfma_f32_16x16x32_bf16 v[122:125], v[146:149], v[214:217], 0
	v_mfma_f32_16x16x32_bf16 v[78:81], v[150:153], v[190:193], v[78:81]
	v_mfma_f32_16x16x32_bf16 v[66:69], v[158:161], v[190:193], v[66:69]
	v_mfma_f32_16x16x32_bf16 v[82:85], v[158:161], v[198:201], v[82:85]
	v_mfma_f32_16x16x32_bf16 v[86:89], v[150:153], v[198:201], v[86:89]
	v_mfma_f32_16x16x32_bf16 v[110:113], v[150:153], v[210:213], v[110:113]
	v_mfma_f32_16x16x32_bf16 v[98:101], v[158:161], v[210:213], v[98:101]
	v_mfma_f32_16x16x32_bf16 v[126:129], v[158:161], v[238:241], v[126:129]
	v_mfma_f32_16x16x32_bf16 v[122:125], v[150:153], v[238:241], v[122:125]
	s_setprio 0
	s_barrier
	s_add_i32 s82, 0, 0x18000
	s_add_i32 s83, 0, 0x1c000
	v_add_u32_e32 v142, s82, v202
	v_add_u32_e32 v158, s83, v202
	ds_read_b128 v[130:133], v142
	ds_read_b128 v[134:137], v142 offset:1024
	ds_read_b128 v[138:141], v142 offset:2048
	ds_read_b128 v[142:145], v142 offset:3072
	ds_read_b128 v[146:149], v158
	ds_read_b128 v[150:153], v158 offset:1024
	ds_read_b128 v[154:157], v158 offset:2048
	ds_read_b128 v[158:161], v158 offset:3072
	s_add_u32 s68, s68, 0x40000
	s_addc_u32 s69, s69, 0
	s_mov_b32 m0, s72
	v_lshl_add_u64 v[244:245], s[68:69], 0, v[164:165]
	ds_read_b128 v[186:189], v204 offset:32768
	ds_read_b128 v[190:193], v204 offset:33792
	ds_read_b128 v[194:197], v204 offset:34816
	ds_read_b128 v[198:201], v204 offset:35840
	ds_read_b128 v[206:209], v204 offset:36864
	ds_read_b128 v[210:213], v204 offset:37888
	ds_read_b128 v[214:217], v204 offset:38912
	ds_read_b128 v[238:241], v204 offset:39936
	global_load_lds_dwordx4 v[244:245], off
	v_lshl_add_u64 v[244:245], s[68:69], 0, v[162:163]
	s_mov_b32 m0, s73
	s_nop 0
	global_load_lds_dwordx4 v[244:245], off
	s_waitcnt vmcnt(8)
	s_waitcnt lgkmcnt(0)
	s_barrier
	s_setprio 1
	s_waitcnt lgkmcnt(0)
	v_mfma_f32_16x16x32_bf16 v[2:5], v[130:133], v[186:189], v[2:5]
	v_mfma_f32_16x16x32_bf16 v[6:9], v[138:141], v[186:189], v[6:9]
	v_mfma_f32_16x16x32_bf16 v[26:29], v[138:141], v[194:197], v[26:29]
	v_mfma_f32_16x16x32_bf16 v[30:33], v[130:133], v[194:197], v[30:33]
	v_mfma_f32_16x16x32_bf16 v[34:37], v[130:133], v[206:209], v[34:37]
	v_mfma_f32_16x16x32_bf16 v[42:45], v[138:141], v[206:209], v[42:45]
	v_mfma_f32_16x16x32_bf16 v[58:61], v[138:141], v[214:217], v[58:61]
	v_mfma_f32_16x16x32_bf16 v[62:65], v[130:133], v[214:217], v[62:65]
	v_mfma_f32_16x16x32_bf16 v[2:5], v[134:137], v[190:193], v[2:5]
	v_mfma_f32_16x16x32_bf16 v[6:9], v[142:145], v[190:193], v[6:9]
	v_mfma_f32_16x16x32_bf16 v[26:29], v[142:145], v[198:201], v[26:29]
	v_mfma_f32_16x16x32_bf16 v[30:33], v[134:137], v[198:201], v[30:33]
	v_mfma_f32_16x16x32_bf16 v[34:37], v[134:137], v[210:213], v[34:37]
	v_mfma_f32_16x16x32_bf16 v[42:45], v[142:145], v[210:213], v[42:45]
	v_mfma_f32_16x16x32_bf16 v[58:61], v[142:145], v[238:241], v[58:61]
	v_mfma_f32_16x16x32_bf16 v[62:65], v[134:137], v[238:241], v[62:65]
	s_setprio 0
	s_setprio 1
	v_mfma_f32_16x16x32_bf16 v[14:17], v[146:149], v[186:189], v[14:17]
	v_mfma_f32_16x16x32_bf16 v[10:13], v[154:157], v[186:189], v[10:13]
	v_mfma_f32_16x16x32_bf16 v[18:21], v[154:157], v[194:197], v[18:21]
	v_mfma_f32_16x16x32_bf16 v[22:25], v[146:149], v[194:197], v[22:25]
	v_mfma_f32_16x16x32_bf16 v[46:49], v[146:149], v[206:209], v[46:49]
	v_mfma_f32_16x16x32_bf16 v[38:41], v[154:157], v[206:209], v[38:41]
	v_mfma_f32_16x16x32_bf16 v[50:53], v[154:157], v[214:217], v[50:53]
	v_mfma_f32_16x16x32_bf16 v[54:57], v[146:149], v[214:217], v[54:57]
	v_mfma_f32_16x16x32_bf16 v[14:17], v[150:153], v[190:193], v[14:17]
	v_mfma_f32_16x16x32_bf16 v[10:13], v[158:161], v[190:193], v[10:13]
	v_mfma_f32_16x16x32_bf16 v[18:21], v[158:161], v[198:201], v[18:21]
	v_mfma_f32_16x16x32_bf16 v[22:25], v[150:153], v[198:201], v[22:25]
	v_mfma_f32_16x16x32_bf16 v[46:49], v[150:153], v[210:213], v[46:49]
	v_mfma_f32_16x16x32_bf16 v[38:41], v[158:161], v[210:213], v[38:41]
	v_mfma_f32_16x16x32_bf16 v[50:53], v[158:161], v[238:241], v[50:53]
	v_mfma_f32_16x16x32_bf16 v[54:57], v[150:153], v[238:241], v[54:57]
	s_setprio 0
	s_barrier
	s_add_i32 s68, s82, s41
	v_lshl_add_u64 v[218:219], v[218:219], 0, s[76:77]
	s_mov_b32 m0, s68
	ds_read_b128 v[186:189], v204 offset:49152
	ds_read_b128 v[190:193], v204 offset:50176
	ds_read_b128 v[194:197], v204 offset:51200
	ds_read_b128 v[198:201], v204 offset:52224
	ds_read_b128 v[206:209], v204 offset:53248
	ds_read_b128 v[210:213], v204 offset:54272
	ds_read_b128 v[214:217], v204 offset:55296
	ds_read_b128 v[238:241], v204 offset:56320
	global_load_lds_dwordx4 v[218:219], off
	s_add_i32 m0, s68, 0x2000
	s_add_u32 s6, s6, 0x40080
	v_lshl_add_u64 v[218:219], v[230:231], 0, s[76:77]
	s_addc_u32 s7, s7, 0
	s_add_i32 s68, s83, s41
	global_load_lds_dwordx4 v[218:219], off
	v_lshl_add_u64 v[218:219], s[6:7], 0, v[164:165]
	s_mov_b32 m0, s68
	s_nop 0
	global_load_lds_dwordx4 v[218:219], off
	v_lshl_add_u64 v[218:219], s[6:7], 0, v[162:163]
	s_add_i32 m0, s68, 0x2000
	s_nop 0
	global_load_lds_dwordx4 v[218:219], off
	v_lshl_add_u64 v[218:219], v[232:233], 0, s[76:77]
	s_mov_b32 m0, s34
	s_nop 0
	global_load_lds_dwordx4 v[218:219], off
	v_lshl_add_u64 v[218:219], v[242:243], 0, s[76:77]
	s_mov_b32 m0, s30
	s_nop 0
	global_load_lds_dwordx4 v[218:219], off
	s_waitcnt vmcnt(8)
	s_waitcnt lgkmcnt(0)
	s_barrier
	s_setprio 1
	s_waitcnt lgkmcnt(0)
	v_mfma_f32_16x16x32_bf16 v[74:77], v[130:133], v[186:189], v[74:77]
	v_mfma_f32_16x16x32_bf16 v[70:73], v[138:141], v[186:189], v[70:73]
	v_mfma_f32_16x16x32_bf16 v[90:93], v[138:141], v[194:197], v[90:93]
	v_mfma_f32_16x16x32_bf16 v[94:97], v[130:133], v[194:197], v[94:97]
	v_mfma_f32_16x16x32_bf16 v[106:109], v[130:133], v[206:209], v[106:109]
	v_mfma_f32_16x16x32_bf16 v[102:105], v[138:141], v[206:209], v[102:105]
	v_mfma_f32_16x16x32_bf16 v[114:117], v[138:141], v[214:217], v[114:117]
	v_mfma_f32_16x16x32_bf16 v[118:121], v[130:133], v[214:217], v[118:121]
	v_mfma_f32_16x16x32_bf16 v[74:77], v[134:137], v[190:193], v[74:77]
	v_mfma_f32_16x16x32_bf16 v[70:73], v[142:145], v[190:193], v[70:73]
	v_mfma_f32_16x16x32_bf16 v[90:93], v[142:145], v[198:201], v[90:93]
	v_mfma_f32_16x16x32_bf16 v[94:97], v[134:137], v[198:201], v[94:97]
	v_mfma_f32_16x16x32_bf16 v[106:109], v[134:137], v[210:213], v[106:109]
	v_mfma_f32_16x16x32_bf16 v[102:105], v[142:145], v[210:213], v[102:105]
	v_mfma_f32_16x16x32_bf16 v[114:117], v[142:145], v[238:241], v[114:117]
	v_mfma_f32_16x16x32_bf16 v[118:121], v[134:137], v[238:241], v[118:121]
	s_setprio 0
	s_setprio 1
	v_mfma_f32_16x16x32_bf16 v[78:81], v[146:149], v[186:189], v[78:81]
	v_mfma_f32_16x16x32_bf16 v[66:69], v[154:157], v[186:189], v[66:69]
	v_mfma_f32_16x16x32_bf16 v[82:85], v[154:157], v[194:197], v[82:85]
	v_mfma_f32_16x16x32_bf16 v[86:89], v[146:149], v[194:197], v[86:89]
	v_mfma_f32_16x16x32_bf16 v[110:113], v[146:149], v[206:209], v[110:113]
	v_mfma_f32_16x16x32_bf16 v[98:101], v[154:157], v[206:209], v[98:101]
	v_mfma_f32_16x16x32_bf16 v[126:129], v[154:157], v[214:217], v[126:129]
	v_mfma_f32_16x16x32_bf16 v[122:125], v[146:149], v[214:217], v[122:125]
	v_mfma_f32_16x16x32_bf16 v[78:81], v[150:153], v[190:193], v[78:81]
	v_mfma_f32_16x16x32_bf16 v[66:69], v[158:161], v[190:193], v[66:69]
	v_mfma_f32_16x16x32_bf16 v[82:85], v[158:161], v[198:201], v[82:85]
	v_mfma_f32_16x16x32_bf16 v[86:89], v[150:153], v[198:201], v[86:89]
	v_mfma_f32_16x16x32_bf16 v[110:113], v[150:153], v[210:213], v[110:113]
	v_mfma_f32_16x16x32_bf16 v[98:101], v[158:161], v[210:213], v[98:101]
	v_mfma_f32_16x16x32_bf16 v[126:129], v[158:161], v[238:241], v[126:129]
	v_mfma_f32_16x16x32_bf16 v[122:125], v[150:153], v[238:241], v[122:125]
	s_setprio 0
	s_barrier
	s_add_i32 s59, s59, 2
	s_add_u32 s4, s4, 0x100
	s_addc_u32 s5, s5, 0
	s_add_u32 s46, s46, 0x100
	s_addc_u32 s57, s57, 0
.LBB0_283:
	s_add_u32 s6, s4, 0xfffc0080
	s_addc_u32 s7, s5, -1
	s_add_i32 s82, 0, 0x10000
	s_cmp_eq_u32 s59, 12
	s_cselect_b32 s69, s20, s7
	s_cselect_b32 s68, s21, s6
	s_cselect_b32 s7, s36, s57
	s_cselect_b32 s6, s37, s46
	s_add_i32 s84, 0, 0x14000
	v_add_u32_e32 v142, s82, v202
	v_add_u32_e32 v158, s84, v202
	ds_read_b128 v[130:133], v142
	ds_read_b128 v[134:137], v142 offset:1024
	ds_read_b128 v[138:141], v142 offset:2048
	ds_read_b128 v[142:145], v142 offset:3072
	ds_read_b128 v[146:149], v158
	ds_read_b128 v[150:153], v158 offset:1024
	ds_read_b128 v[154:157], v158 offset:2048
	ds_read_b128 v[158:161], v158 offset:3072
	v_lshl_add_u64 v[218:219], s[4:5], 0, v[182:183]
	s_add_i32 m0, s87, 0xc000
	ds_read_b128 v[186:189], v204
	ds_read_b128 v[190:193], v204 offset:1024
	ds_read_b128 v[194:197], v204 offset:2048
	ds_read_b128 v[198:201], v204 offset:3072
	ds_read_b128 v[206:209], v204 offset:4096
	ds_read_b128 v[210:213], v204 offset:5120
	ds_read_b128 v[214:217], v204 offset:6144
	ds_read_b128 v[238:241], v204 offset:7168
	global_load_lds_dwordx4 v[218:219], off
	v_lshl_add_u64 v[218:219], s[4:5], 0, v[184:185]
	s_add_i32 m0, s87, 0xe000
	s_nop 0
	global_load_lds_dwordx4 v[218:219], off
	s_waitcnt vmcnt(8)
	s_waitcnt lgkmcnt(0)
	s_barrier
	s_setprio 1
	s_waitcnt lgkmcnt(0)
	v_mfma_f32_16x16x32_bf16 v[2:5], v[130:133], v[186:189], v[2:5]
	v_mfma_f32_16x16x32_bf16 v[6:9], v[138:141], v[186:189], v[6:9]
	v_mfma_f32_16x16x32_bf16 v[26:29], v[138:141], v[194:197], v[26:29]
	v_mfma_f32_16x16x32_bf16 v[30:33], v[130:133], v[194:197], v[30:33]
	v_mfma_f32_16x16x32_bf16 v[34:37], v[130:133], v[206:209], v[34:37]
	v_mfma_f32_16x16x32_bf16 v[42:45], v[138:141], v[206:209], v[42:45]
	v_mfma_f32_16x16x32_bf16 v[58:61], v[138:141], v[214:217], v[58:61]
	v_mfma_f32_16x16x32_bf16 v[62:65], v[130:133], v[214:217], v[62:65]
	v_mfma_f32_16x16x32_bf16 v[2:5], v[134:137], v[190:193], v[2:5]
	v_mfma_f32_16x16x32_bf16 v[6:9], v[142:145], v[190:193], v[6:9]
	v_mfma_f32_16x16x32_bf16 v[26:29], v[142:145], v[198:201], v[26:29]
	v_mfma_f32_16x16x32_bf16 v[30:33], v[134:137], v[198:201], v[30:33]
	v_mfma_f32_16x16x32_bf16 v[34:37], v[134:137], v[210:213], v[34:37]
	v_mfma_f32_16x16x32_bf16 v[42:45], v[142:145], v[210:213], v[42:45]
	v_mfma_f32_16x16x32_bf16 v[58:61], v[142:145], v[238:241], v[58:61]
	v_mfma_f32_16x16x32_bf16 v[62:65], v[134:137], v[238:241], v[62:65]
	s_setprio 0
	s_setprio 1
	v_mfma_f32_16x16x32_bf16 v[14:17], v[146:149], v[186:189], v[14:17]
	v_mfma_f32_16x16x32_bf16 v[10:13], v[154:157], v[186:189], v[10:13]
	v_mfma_f32_16x16x32_bf16 v[18:21], v[154:157], v[194:197], v[18:21]
	v_mfma_f32_16x16x32_bf16 v[22:25], v[146:149], v[194:197], v[22:25]
	v_mfma_f32_16x16x32_bf16 v[46:49], v[146:149], v[206:209], v[46:49]
	v_mfma_f32_16x16x32_bf16 v[38:41], v[154:157], v[206:209], v[38:41]
	v_mfma_f32_16x16x32_bf16 v[50:53], v[154:157], v[214:217], v[50:53]
	v_mfma_f32_16x16x32_bf16 v[54:57], v[146:149], v[214:217], v[54:57]
	v_mfma_f32_16x16x32_bf16 v[14:17], v[150:153], v[190:193], v[14:17]
	v_mfma_f32_16x16x32_bf16 v[10:13], v[158:161], v[190:193], v[10:13]
	v_mfma_f32_16x16x32_bf16 v[18:21], v[158:161], v[198:201], v[18:21]
	v_mfma_f32_16x16x32_bf16 v[22:25], v[150:153], v[198:201], v[22:25]
	v_mfma_f32_16x16x32_bf16 v[46:49], v[150:153], v[210:213], v[46:49]
	v_mfma_f32_16x16x32_bf16 v[38:41], v[158:161], v[210:213], v[38:41]
	v_mfma_f32_16x16x32_bf16 v[50:53], v[158:161], v[238:241], v[50:53]
	v_mfma_f32_16x16x32_bf16 v[54:57], v[150:153], v[238:241], v[54:57]
	s_setprio 0
	s_barrier
	s_add_i32 s82, s82, s41
	v_lshl_add_u64 v[218:219], s[6:7], 0, v[164:165]
	s_mov_b32 m0, s82
	ds_read_b128 v[186:189], v204 offset:16384
	ds_read_b128 v[190:193], v204 offset:17408
	ds_read_b128 v[194:197], v204 offset:18432
	ds_read_b128 v[198:201], v204 offset:19456
	ds_read_b128 v[206:209], v204 offset:20480
	ds_read_b128 v[210:213], v204 offset:21504
	ds_read_b128 v[214:217], v204 offset:22528
	ds_read_b128 v[238:241], v204 offset:23552
	global_load_lds_dwordx4 v[218:219], off
	s_add_i32 m0, s82, 0x2000
	s_add_u32 s82, s6, 0x40000
	v_lshl_add_u64 v[230:231], s[6:7], 0, v[162:163]
	s_addc_u32 s83, s7, 0
	s_add_i32 s84, s84, s41
	global_load_lds_dwordx4 v[230:231], off
	v_lshl_add_u64 v[232:233], s[82:83], 0, v[164:165]
	s_mov_b32 m0, s84
	v_lshl_add_u64 v[242:243], s[68:69], 0, v[162:163]
	global_load_lds_dwordx4 v[232:233], off
	v_lshl_add_u64 v[232:233], s[82:83], 0, v[162:163]
	s_add_i32 m0, s84, 0x2000
	s_nop 0
	global_load_lds_dwordx4 v[232:233], off
	v_lshl_add_u64 v[232:233], s[68:69], 0, v[164:165]
	s_mov_b32 m0, s87
	s_nop 0
	global_load_lds_dwordx4 v[232:233], off
	s_mov_b32 m0, s75
	s_nop 0
	global_load_lds_dwordx4 v[242:243], off
	s_waitcnt vmcnt(8)
	s_waitcnt lgkmcnt(0)
	s_barrier
	s_setprio 1
	s_waitcnt lgkmcnt(0)
	v_mfma_f32_16x16x32_bf16 v[74:77], v[130:133], v[186:189], v[74:77]
	v_mfma_f32_16x16x32_bf16 v[70:73], v[138:141], v[186:189], v[70:73]
	v_mfma_f32_16x16x32_bf16 v[90:93], v[138:141], v[194:197], v[90:93]
	v_mfma_f32_16x16x32_bf16 v[94:97], v[130:133], v[194:197], v[94:97]
	v_mfma_f32_16x16x32_bf16 v[106:109], v[130:133], v[206:209], v[106:109]
	v_mfma_f32_16x16x32_bf16 v[102:105], v[138:141], v[206:209], v[102:105]
	v_mfma_f32_16x16x32_bf16 v[114:117], v[138:141], v[214:217], v[114:117]
	v_mfma_f32_16x16x32_bf16 v[118:121], v[130:133], v[214:217], v[118:121]
	v_mfma_f32_16x16x32_bf16 v[74:77], v[134:137], v[190:193], v[74:77]
	v_mfma_f32_16x16x32_bf16 v[70:73], v[142:145], v[190:193], v[70:73]
	v_mfma_f32_16x16x32_bf16 v[90:93], v[142:145], v[198:201], v[90:93]
	v_mfma_f32_16x16x32_bf16 v[94:97], v[134:137], v[198:201], v[94:97]
	v_mfma_f32_16x16x32_bf16 v[106:109], v[134:137], v[210:213], v[106:109]
	v_mfma_f32_16x16x32_bf16 v[102:105], v[142:145], v[210:213], v[102:105]
	v_mfma_f32_16x16x32_bf16 v[114:117], v[142:145], v[238:241], v[114:117]
	v_mfma_f32_16x16x32_bf16 v[118:121], v[134:137], v[238:241], v[118:121]
	s_setprio 0
	s_setprio 1
	v_mfma_f32_16x16x32_bf16 v[78:81], v[146:149], v[186:189], v[78:81]
	v_mfma_f32_16x16x32_bf16 v[66:69], v[154:157], v[186:189], v[66:69]
	v_mfma_f32_16x16x32_bf16 v[82:85], v[154:157], v[194:197], v[82:85]
	v_mfma_f32_16x16x32_bf16 v[86:89], v[146:149], v[194:197], v[86:89]
	v_mfma_f32_16x16x32_bf16 v[110:113], v[146:149], v[206:209], v[110:113]
	v_mfma_f32_16x16x32_bf16 v[98:101], v[154:157], v[206:209], v[98:101]
	v_mfma_f32_16x16x32_bf16 v[126:129], v[154:157], v[214:217], v[126:129]
	v_mfma_f32_16x16x32_bf16 v[122:125], v[146:149], v[214:217], v[122:125]
	v_mfma_f32_16x16x32_bf16 v[78:81], v[150:153], v[190:193], v[78:81]
	v_mfma_f32_16x16x32_bf16 v[66:69], v[158:161], v[190:193], v[66:69]
	v_mfma_f32_16x16x32_bf16 v[82:85], v[158:161], v[198:201], v[82:85]
	v_mfma_f32_16x16x32_bf16 v[86:89], v[150:153], v[198:201], v[86:89]
	v_mfma_f32_16x16x32_bf16 v[110:113], v[150:153], v[210:213], v[110:113]
	v_mfma_f32_16x16x32_bf16 v[98:101], v[158:161], v[210:213], v[98:101]
	v_mfma_f32_16x16x32_bf16 v[126:129], v[158:161], v[238:241], v[126:129]
	v_mfma_f32_16x16x32_bf16 v[122:125], v[150:153], v[238:241], v[122:125]
	s_setprio 0
	s_barrier
	s_add_i32 s82, 0, 0x18000
	s_add_i32 s83, 0, 0x1c000
	v_add_u32_e32 v142, s82, v202
	v_add_u32_e32 v158, s83, v202
	ds_read_b128 v[130:133], v142
	ds_read_b128 v[134:137], v142 offset:1024
	ds_read_b128 v[138:141], v142 offset:2048
	ds_read_b128 v[142:145], v142 offset:3072
	ds_read_b128 v[146:149], v158
	ds_read_b128 v[150:153], v158 offset:1024
	ds_read_b128 v[154:157], v158 offset:2048
	ds_read_b128 v[158:161], v158 offset:3072
	s_add_u32 s68, s68, 0x40000
	s_addc_u32 s69, s69, 0
	s_mov_b32 m0, s72
	v_lshl_add_u64 v[244:245], s[68:69], 0, v[164:165]
	ds_read_b128 v[186:189], v204 offset:32768
	ds_read_b128 v[190:193], v204 offset:33792
	ds_read_b128 v[194:197], v204 offset:34816
	ds_read_b128 v[198:201], v204 offset:35840
	ds_read_b128 v[206:209], v204 offset:36864
	ds_read_b128 v[210:213], v204 offset:37888
	ds_read_b128 v[214:217], v204 offset:38912
	ds_read_b128 v[238:241], v204 offset:39936
	global_load_lds_dwordx4 v[244:245], off
	v_lshl_add_u64 v[244:245], s[68:69], 0, v[162:163]
	s_mov_b32 m0, s73
	s_nop 0
	global_load_lds_dwordx4 v[244:245], off
	s_waitcnt vmcnt(8)
	s_waitcnt lgkmcnt(0)
	s_barrier
	s_setprio 1
	s_waitcnt lgkmcnt(0)
	v_mfma_f32_16x16x32_bf16 v[2:5], v[130:133], v[186:189], v[2:5]
	v_mfma_f32_16x16x32_bf16 v[6:9], v[138:141], v[186:189], v[6:9]
	v_mfma_f32_16x16x32_bf16 v[26:29], v[138:141], v[194:197], v[26:29]
	v_mfma_f32_16x16x32_bf16 v[30:33], v[130:133], v[194:197], v[30:33]
	v_mfma_f32_16x16x32_bf16 v[34:37], v[130:133], v[206:209], v[34:37]
	v_mfma_f32_16x16x32_bf16 v[42:45], v[138:141], v[206:209], v[42:45]
	v_mfma_f32_16x16x32_bf16 v[58:61], v[138:141], v[214:217], v[58:61]
	v_mfma_f32_16x16x32_bf16 v[62:65], v[130:133], v[214:217], v[62:65]
	v_mfma_f32_16x16x32_bf16 v[2:5], v[134:137], v[190:193], v[2:5]
	v_mfma_f32_16x16x32_bf16 v[6:9], v[142:145], v[190:193], v[6:9]
	v_mfma_f32_16x16x32_bf16 v[26:29], v[142:145], v[198:201], v[26:29]
	v_mfma_f32_16x16x32_bf16 v[30:33], v[134:137], v[198:201], v[30:33]
	v_mfma_f32_16x16x32_bf16 v[34:37], v[134:137], v[210:213], v[34:37]
	v_mfma_f32_16x16x32_bf16 v[42:45], v[142:145], v[210:213], v[42:45]
	v_mfma_f32_16x16x32_bf16 v[58:61], v[142:145], v[238:241], v[58:61]
	v_mfma_f32_16x16x32_bf16 v[62:65], v[134:137], v[238:241], v[62:65]
	s_setprio 0
	s_setprio 1
	v_mfma_f32_16x16x32_bf16 v[14:17], v[146:149], v[186:189], v[14:17]
	v_mfma_f32_16x16x32_bf16 v[10:13], v[154:157], v[186:189], v[10:13]
	v_mfma_f32_16x16x32_bf16 v[18:21], v[154:157], v[194:197], v[18:21]
	v_mfma_f32_16x16x32_bf16 v[22:25], v[146:149], v[194:197], v[22:25]
	v_mfma_f32_16x16x32_bf16 v[46:49], v[146:149], v[206:209], v[46:49]
	v_mfma_f32_16x16x32_bf16 v[38:41], v[154:157], v[206:209], v[38:41]
	v_mfma_f32_16x16x32_bf16 v[50:53], v[154:157], v[214:217], v[50:53]
	v_mfma_f32_16x16x32_bf16 v[54:57], v[146:149], v[214:217], v[54:57]
	v_mfma_f32_16x16x32_bf16 v[14:17], v[150:153], v[190:193], v[14:17]
	v_mfma_f32_16x16x32_bf16 v[10:13], v[158:161], v[190:193], v[10:13]
	v_mfma_f32_16x16x32_bf16 v[18:21], v[158:161], v[198:201], v[18:21]
	v_mfma_f32_16x16x32_bf16 v[22:25], v[150:153], v[198:201], v[22:25]
	v_mfma_f32_16x16x32_bf16 v[46:49], v[150:153], v[210:213], v[46:49]
	v_mfma_f32_16x16x32_bf16 v[38:41], v[158:161], v[210:213], v[38:41]
	v_mfma_f32_16x16x32_bf16 v[50:53], v[158:161], v[238:241], v[50:53]
	v_mfma_f32_16x16x32_bf16 v[54:57], v[150:153], v[238:241], v[54:57]
	s_setprio 0
	s_barrier
	s_add_i32 s68, s82, s41
	v_lshl_add_u64 v[218:219], v[218:219], 0, s[76:77]
	s_mov_b32 m0, s68
	ds_read_b128 v[186:189], v204 offset:49152
	ds_read_b128 v[190:193], v204 offset:50176
	ds_read_b128 v[194:197], v204 offset:51200
	ds_read_b128 v[198:201], v204 offset:52224
	ds_read_b128 v[206:209], v204 offset:53248
	ds_read_b128 v[210:213], v204 offset:54272
	ds_read_b128 v[214:217], v204 offset:55296
	ds_read_b128 v[238:241], v204 offset:56320
	global_load_lds_dwordx4 v[218:219], off
	s_add_i32 m0, s68, 0x2000
	s_add_u32 s6, s6, 0x40080
	v_lshl_add_u64 v[218:219], v[230:231], 0, s[76:77]
	s_addc_u32 s7, s7, 0
	s_add_i32 s68, s83, s41
	global_load_lds_dwordx4 v[218:219], off
	v_lshl_add_u64 v[218:219], s[6:7], 0, v[164:165]
	s_mov_b32 m0, s68
	s_nop 0
	global_load_lds_dwordx4 v[218:219], off
	v_lshl_add_u64 v[218:219], s[6:7], 0, v[162:163]
	s_add_i32 m0, s68, 0x2000
	s_nop 0
	global_load_lds_dwordx4 v[218:219], off
	v_lshl_add_u64 v[218:219], v[232:233], 0, s[76:77]
	s_mov_b32 m0, s34
	s_nop 0
	global_load_lds_dwordx4 v[218:219], off
	v_lshl_add_u64 v[218:219], v[242:243], 0, s[76:77]
	s_mov_b32 m0, s30
	s_nop 0
	global_load_lds_dwordx4 v[218:219], off
	s_waitcnt vmcnt(8)
	s_waitcnt lgkmcnt(0)
	s_barrier
	s_setprio 1
	s_waitcnt lgkmcnt(0)
	v_mfma_f32_16x16x32_bf16 v[74:77], v[130:133], v[186:189], v[74:77]
	v_mfma_f32_16x16x32_bf16 v[70:73], v[138:141], v[186:189], v[70:73]
	v_mfma_f32_16x16x32_bf16 v[90:93], v[138:141], v[194:197], v[90:93]
	v_mfma_f32_16x16x32_bf16 v[94:97], v[130:133], v[194:197], v[94:97]
	v_mfma_f32_16x16x32_bf16 v[106:109], v[130:133], v[206:209], v[106:109]
	v_mfma_f32_16x16x32_bf16 v[102:105], v[138:141], v[206:209], v[102:105]
	v_mfma_f32_16x16x32_bf16 v[114:117], v[138:141], v[214:217], v[114:117]
	v_mfma_f32_16x16x32_bf16 v[118:121], v[130:133], v[214:217], v[118:121]
	v_mfma_f32_16x16x32_bf16 v[74:77], v[134:137], v[190:193], v[74:77]
	v_mfma_f32_16x16x32_bf16 v[70:73], v[142:145], v[190:193], v[70:73]
	v_mfma_f32_16x16x32_bf16 v[90:93], v[142:145], v[198:201], v[90:93]
	v_mfma_f32_16x16x32_bf16 v[94:97], v[134:137], v[198:201], v[94:97]
	v_mfma_f32_16x16x32_bf16 v[106:109], v[134:137], v[210:213], v[106:109]
	v_mfma_f32_16x16x32_bf16 v[102:105], v[142:145], v[210:213], v[102:105]
	v_mfma_f32_16x16x32_bf16 v[114:117], v[142:145], v[238:241], v[114:117]
	v_mfma_f32_16x16x32_bf16 v[118:121], v[134:137], v[238:241], v[118:121]
	s_setprio 0
	s_setprio 1
	v_mfma_f32_16x16x32_bf16 v[78:81], v[146:149], v[186:189], v[78:81]
	v_mfma_f32_16x16x32_bf16 v[66:69], v[154:157], v[186:189], v[66:69]
	v_mfma_f32_16x16x32_bf16 v[82:85], v[154:157], v[194:197], v[82:85]
	v_mfma_f32_16x16x32_bf16 v[86:89], v[146:149], v[194:197], v[86:89]
	v_mfma_f32_16x16x32_bf16 v[110:113], v[146:149], v[206:209], v[110:113]
	v_mfma_f32_16x16x32_bf16 v[98:101], v[154:157], v[206:209], v[98:101]
	v_mfma_f32_16x16x32_bf16 v[126:129], v[154:157], v[214:217], v[126:129]
	v_mfma_f32_16x16x32_bf16 v[122:125], v[146:149], v[214:217], v[122:125]
	v_mfma_f32_16x16x32_bf16 v[78:81], v[150:153], v[190:193], v[78:81]
	v_mfma_f32_16x16x32_bf16 v[66:69], v[158:161], v[190:193], v[66:69]
	v_mfma_f32_16x16x32_bf16 v[82:85], v[158:161], v[198:201], v[82:85]
	v_mfma_f32_16x16x32_bf16 v[86:89], v[150:153], v[198:201], v[86:89]
	v_mfma_f32_16x16x32_bf16 v[110:113], v[150:153], v[210:213], v[110:113]
	v_mfma_f32_16x16x32_bf16 v[98:101], v[158:161], v[210:213], v[98:101]
	v_mfma_f32_16x16x32_bf16 v[126:129], v[158:161], v[238:241], v[126:129]
	v_mfma_f32_16x16x32_bf16 v[122:125], v[150:153], v[238:241], v[122:125]
	s_setprio 0
	s_barrier
	s_add_i32 s59, s59, 2
	s_add_u32 s4, s4, 0x100
	s_addc_u32 s5, s5, 0
	s_add_u32 s46, s46, 0x100
	s_addc_u32 s57, s57, 0
	s_cmp_gt_u32 s59, 13
	s_cbranch_scc0 .LBB0_283
	s_and_b64 vcc, exec, s[42:43]
	s_cbranch_vccz .LBB0_286
	s_barrier

.LBB0_670:
	s_add_u32 s6, s58, 0x80
	s_addc_u32 s7, s59, 0
	s_add_u32 s21, s56, 0x100
	s_addc_u32 s26, s57, 0
	s_mov_b32 s27, 0
	s_add_i32 s46, s27, 2
	s_add_u32 s0, s6, 0x80
	s_addc_u32 s56, s7, 0
	s_add_i32 vcc_lo, 0, 0x10000
	s_cmp_eq_u32 s72, s27
	s_cselect_b32 s57, s51, s56
	s_cselect_b32 s56, s50, s0
	s_cselect_b32 s59, s53, s26
	s_cselect_b32 s58, s52, s21
	s_add_i32 s0, 0, 0x14000
	v_add_u32_e32 v70, vcc_lo, v237
	v_add_u32_e32 v94, s0, v237
	ds_read_b128 v[58:61], v70
	ds_read_b128 v[62:65], v70 offset:1024
	ds_read_b128 v[66:69], v70 offset:2048
	ds_read_b128 v[70:73], v70 offset:3072
	ds_read_b128 v[82:85], v94
	ds_read_b128 v[86:89], v94 offset:1024
	ds_read_b128 v[90:93], v94 offset:2048
	ds_read_b128 v[94:97], v94 offset:3072
	v_lshl_add_u64 v[210:211], s[6:7], 0, v[194:195]
	s_add_i32 m0, s64, 0xc000
	ds_read_b128 v[162:165], v239
	ds_read_b128 v[166:169], v239 offset:1024
	ds_read_b128 v[170:173], v239 offset:2048
	ds_read_b128 v[174:177], v239 offset:3072
	ds_read_b128 v[178:181], v239 offset:4096
	ds_read_b128 v[198:201], v239 offset:5120
	ds_read_b128 v[202:205], v239 offset:6144
	ds_read_b128 v[206:209], v239 offset:7168
	global_load_lds_dwordx4 v[210:211], off
	v_lshl_add_u64 v[210:211], s[6:7], 0, v[196:197]
	s_add_i32 m0, s64, 0xe000
	s_nop 0
	global_load_lds_dwordx4 v[210:211], off
	s_waitcnt vmcnt(8)
	s_waitcnt lgkmcnt(0)
	s_barrier
	s_setprio 1
	s_waitcnt lgkmcnt(0)
	v_mfma_f32_16x16x32_bf16 v[158:161], v[58:61], v[162:165], 0
	v_mfma_f32_16x16x32_bf16 v[154:157], v[66:69], v[162:165], 0
	v_mfma_f32_16x16x32_bf16 v[138:141], v[66:69], v[170:173], 0
	v_mfma_f32_16x16x32_bf16 v[142:145], v[58:61], v[170:173], 0
	v_mfma_f32_16x16x32_bf16 v[126:129], v[58:61], v[178:181], 0
	v_mfma_f32_16x16x32_bf16 v[122:125], v[66:69], v[178:181], 0
	v_mfma_f32_16x16x32_bf16 v[106:109], v[66:69], v[202:205], 0
	v_mfma_f32_16x16x32_bf16 v[110:113], v[58:61], v[202:205], 0
	v_mfma_f32_16x16x32_bf16 v[158:161], v[62:65], v[166:169], v[158:161]
	v_mfma_f32_16x16x32_bf16 v[154:157], v[70:73], v[166:169], v[154:157]
	v_mfma_f32_16x16x32_bf16 v[138:141], v[70:73], v[174:177], v[138:141]
	v_mfma_f32_16x16x32_bf16 v[142:145], v[62:65], v[174:177], v[142:145]
	v_mfma_f32_16x16x32_bf16 v[126:129], v[62:65], v[198:201], v[126:129]
	v_mfma_f32_16x16x32_bf16 v[122:125], v[70:73], v[198:201], v[122:125]
	v_mfma_f32_16x16x32_bf16 v[106:109], v[70:73], v[206:209], v[106:109]
	v_mfma_f32_16x16x32_bf16 v[110:113], v[62:65], v[206:209], v[110:113]
	s_setprio 0
	s_setprio 1
	v_mfma_f32_16x16x32_bf16 v[150:153], v[82:85], v[162:165], 0
	v_mfma_f32_16x16x32_bf16 v[146:149], v[90:93], v[162:165], 0
	v_mfma_f32_16x16x32_bf16 v[130:133], v[90:93], v[170:173], 0
	v_mfma_f32_16x16x32_bf16 v[134:137], v[82:85], v[170:173], 0
	v_mfma_f32_16x16x32_bf16 v[118:121], v[82:85], v[178:181], 0
	v_mfma_f32_16x16x32_bf16 v[114:117], v[90:93], v[178:181], 0
	v_mfma_f32_16x16x32_bf16 v[98:101], v[90:93], v[202:205], 0
	v_mfma_f32_16x16x32_bf16 v[102:105], v[82:85], v[202:205], 0
	v_mfma_f32_16x16x32_bf16 v[150:153], v[86:89], v[166:169], v[150:153]
	v_mfma_f32_16x16x32_bf16 v[146:149], v[94:97], v[166:169], v[146:149]
	v_mfma_f32_16x16x32_bf16 v[130:133], v[94:97], v[174:177], v[130:133]
	v_mfma_f32_16x16x32_bf16 v[134:137], v[86:89], v[174:177], v[134:137]
	v_mfma_f32_16x16x32_bf16 v[118:121], v[86:89], v[198:201], v[118:121]
	v_mfma_f32_16x16x32_bf16 v[114:117], v[94:97], v[198:201], v[114:117]
	v_mfma_f32_16x16x32_bf16 v[98:101], v[94:97], v[206:209], v[98:101]
	v_mfma_f32_16x16x32_bf16 v[102:105], v[86:89], v[206:209], v[102:105]
	s_setprio 0
	s_barrier
	s_add_i32 s27, vcc_lo, s61
	v_lshl_add_u64 v[210:211], s[58:59], 0, v[186:187]
	s_mov_b32 m0, s27
	ds_read_b128 v[162:165], v239 offset:16384
	ds_read_b128 v[166:169], v239 offset:17408
	ds_read_b128 v[170:173], v239 offset:18432
	ds_read_b128 v[174:177], v239 offset:19456
	ds_read_b128 v[178:181], v239 offset:20480
	ds_read_b128 v[198:201], v239 offset:21504
	ds_read_b128 v[202:205], v239 offset:22528
	ds_read_b128 v[206:209], v239 offset:23552
	global_load_lds_dwordx4 v[210:211], off
	s_add_i32 m0, s27, 0x2000
	v_lshl_add_u64 v[212:213], s[58:59], 0, v[182:183]
	s_add_u32 s58, s58, s12
	s_addc_u32 s59, s59, 0
	s_add_i32 s0, s0, s61
	global_load_lds_dwordx4 v[212:213], off
	v_lshl_add_u64 v[214:215], s[58:59], 0, v[186:187]
	s_mov_b32 m0, s0
	v_lshl_add_u64 v[216:217], s[58:59], 0, v[182:183]
	global_load_lds_dwordx4 v[214:215], off
	s_add_i32 m0, s0, 0x2000
	v_lshl_add_u64 v[218:219], s[56:57], 0, v[188:189]
	global_load_lds_dwordx4 v[216:217], off
	s_mov_b32 m0, s64
	v_lshl_add_u64 v[230:231], s[56:57], 0, v[184:185]
	global_load_lds_dwordx4 v[218:219], off
	s_mov_b32 m0, s65
	s_nop 0
	global_load_lds_dwordx4 v[230:231], off
	s_waitcnt vmcnt(8)
	s_waitcnt lgkmcnt(0)
	s_barrier
	s_setprio 1
	s_waitcnt lgkmcnt(0)
	v_mfma_f32_16x16x32_bf16 v[78:81], v[58:61], v[162:165], 0
	v_mfma_f32_16x16x32_bf16 v[74:77], v[66:69], v[162:165], 0
	v_mfma_f32_16x16x32_bf16 v[42:45], v[66:69], v[170:173], 0
	v_mfma_f32_16x16x32_bf16 v[46:49], v[58:61], v[170:173], 0
	v_mfma_f32_16x16x32_bf16 v[30:33], v[58:61], v[178:181], 0
	v_mfma_f32_16x16x32_bf16 v[26:29], v[66:69], v[178:181], 0
	v_mfma_f32_16x16x32_bf16 v[10:13], v[66:69], v[202:205], 0
	v_mfma_f32_16x16x32_bf16 v[14:17], v[58:61], v[202:205], 0
	v_mfma_f32_16x16x32_bf16 v[78:81], v[62:65], v[166:169], v[78:81]
	v_mfma_f32_16x16x32_bf16 v[74:77], v[70:73], v[166:169], v[74:77]
	v_mfma_f32_16x16x32_bf16 v[42:45], v[70:73], v[174:177], v[42:45]
	v_mfma_f32_16x16x32_bf16 v[46:49], v[62:65], v[174:177], v[46:49]
	v_mfma_f32_16x16x32_bf16 v[30:33], v[62:65], v[198:201], v[30:33]
	v_mfma_f32_16x16x32_bf16 v[26:29], v[70:73], v[198:201], v[26:29]
	v_mfma_f32_16x16x32_bf16 v[10:13], v[70:73], v[206:209], v[10:13]
	v_mfma_f32_16x16x32_bf16 v[14:17], v[62:65], v[206:209], v[14:17]
	s_setprio 0
	s_setprio 1
	v_mfma_f32_16x16x32_bf16 v[54:57], v[82:85], v[162:165], 0
	v_mfma_f32_16x16x32_bf16 v[50:53], v[90:93], v[162:165], 0
	v_mfma_f32_16x16x32_bf16 v[34:37], v[90:93], v[170:173], 0
	v_mfma_f32_16x16x32_bf16 v[38:41], v[82:85], v[170:173], 0
	v_mfma_f32_16x16x32_bf16 v[22:25], v[82:85], v[178:181], 0
	v_mfma_f32_16x16x32_bf16 v[18:21], v[90:93], v[178:181], 0
	v_mfma_f32_16x16x32_bf16 v[2:5], v[90:93], v[202:205], 0
	v_mfma_f32_16x16x32_bf16 v[6:9], v[82:85], v[202:205], 0
	v_mfma_f32_16x16x32_bf16 v[54:57], v[86:89], v[166:169], v[54:57]
	v_mfma_f32_16x16x32_bf16 v[50:53], v[94:97], v[166:169], v[50:53]
	v_mfma_f32_16x16x32_bf16 v[34:37], v[94:97], v[174:177], v[34:37]
	v_mfma_f32_16x16x32_bf16 v[38:41], v[86:89], v[174:177], v[38:41]
	v_mfma_f32_16x16x32_bf16 v[22:25], v[86:89], v[198:201], v[22:25]
	v_mfma_f32_16x16x32_bf16 v[18:21], v[94:97], v[198:201], v[18:21]
	v_mfma_f32_16x16x32_bf16 v[2:5], v[94:97], v[206:209], v[2:5]
	v_mfma_f32_16x16x32_bf16 v[6:9], v[86:89], v[206:209], v[6:9]
	s_setprio 0
	s_barrier
	s_add_i32 s0, 0, 0x18000
	s_add_i32 s27, 0, 0x1c000
	v_add_u32_e32 v70, s0, v237
	v_add_u32_e32 v94, s27, v237
	ds_read_b128 v[58:61], v70
	ds_read_b128 v[62:65], v70 offset:1024
	ds_read_b128 v[66:69], v70 offset:2048
	ds_read_b128 v[70:73], v70 offset:3072
	ds_read_b128 v[82:85], v94
	ds_read_b128 v[86:89], v94 offset:1024
	ds_read_b128 v[90:93], v94 offset:2048
	ds_read_b128 v[94:97], v94 offset:3072
	s_add_u32 s56, s56, s12
	s_addc_u32 s57, s57, 0
	s_mov_b32 m0, s66
	v_lshl_add_u64 v[232:233], s[56:57], 0, v[188:189]
	ds_read_b128 v[162:165], v239 offset:32768
	ds_read_b128 v[166:169], v239 offset:33792
	ds_read_b128 v[170:173], v239 offset:34816
	ds_read_b128 v[174:177], v239 offset:35840
	ds_read_b128 v[178:181], v239 offset:36864
	ds_read_b128 v[198:201], v239 offset:37888
	ds_read_b128 v[202:205], v239 offset:38912
	ds_read_b128 v[206:209], v239 offset:39936
	global_load_lds_dwordx4 v[232:233], off
	v_lshl_add_u64 v[232:233], s[56:57], 0, v[184:185]
	s_mov_b32 m0, s67
	s_nop 0
	global_load_lds_dwordx4 v[232:233], off
	s_waitcnt vmcnt(8)
	s_waitcnt lgkmcnt(0)
	s_barrier
	s_setprio 1
	s_waitcnt lgkmcnt(0)
	v_mfma_f32_16x16x32_bf16 v[158:161], v[58:61], v[162:165], v[158:161]
	v_mfma_f32_16x16x32_bf16 v[154:157], v[66:69], v[162:165], v[154:157]
	v_mfma_f32_16x16x32_bf16 v[138:141], v[66:69], v[170:173], v[138:141]
	v_mfma_f32_16x16x32_bf16 v[142:145], v[58:61], v[170:173], v[142:145]
	v_mfma_f32_16x16x32_bf16 v[126:129], v[58:61], v[178:181], v[126:129]
	v_mfma_f32_16x16x32_bf16 v[122:125], v[66:69], v[178:181], v[122:125]
	v_mfma_f32_16x16x32_bf16 v[106:109], v[66:69], v[202:205], v[106:109]
	v_mfma_f32_16x16x32_bf16 v[110:113], v[58:61], v[202:205], v[110:113]
	v_mfma_f32_16x16x32_bf16 v[158:161], v[62:65], v[166:169], v[158:161]
	v_mfma_f32_16x16x32_bf16 v[154:157], v[70:73], v[166:169], v[154:157]
	v_mfma_f32_16x16x32_bf16 v[138:141], v[70:73], v[174:177], v[138:141]
	v_mfma_f32_16x16x32_bf16 v[142:145], v[62:65], v[174:177], v[142:145]
	v_mfma_f32_16x16x32_bf16 v[126:129], v[62:65], v[198:201], v[126:129]
	v_mfma_f32_16x16x32_bf16 v[122:125], v[70:73], v[198:201], v[122:125]
	v_mfma_f32_16x16x32_bf16 v[106:109], v[70:73], v[206:209], v[106:109]
	v_mfma_f32_16x16x32_bf16 v[110:113], v[62:65], v[206:209], v[110:113]
	s_setprio 0
	s_setprio 1
	v_mfma_f32_16x16x32_bf16 v[150:153], v[82:85], v[162:165], v[150:153]
	v_mfma_f32_16x16x32_bf16 v[146:149], v[90:93], v[162:165], v[146:149]
	v_mfma_f32_16x16x32_bf16 v[130:133], v[90:93], v[170:173], v[130:133]
	v_mfma_f32_16x16x32_bf16 v[134:137], v[82:85], v[170:173], v[134:137]
	v_mfma_f32_16x16x32_bf16 v[118:121], v[82:85], v[178:181], v[118:121]
	v_mfma_f32_16x16x32_bf16 v[114:117], v[90:93], v[178:181], v[114:117]
	v_mfma_f32_16x16x32_bf16 v[98:101], v[90:93], v[202:205], v[98:101]
	v_mfma_f32_16x16x32_bf16 v[102:105], v[82:85], v[202:205], v[102:105]
	v_mfma_f32_16x16x32_bf16 v[150:153], v[86:89], v[166:169], v[150:153]
	v_mfma_f32_16x16x32_bf16 v[146:149], v[94:97], v[166:169], v[146:149]
	v_mfma_f32_16x16x32_bf16 v[130:133], v[94:97], v[174:177], v[130:133]
	v_mfma_f32_16x16x32_bf16 v[134:137], v[86:89], v[174:177], v[134:137]
	v_mfma_f32_16x16x32_bf16 v[118:121], v[86:89], v[198:201], v[118:121]
	v_mfma_f32_16x16x32_bf16 v[114:117], v[94:97], v[198:201], v[114:117]
	v_mfma_f32_16x16x32_bf16 v[98:101], v[94:97], v[206:209], v[98:101]
	v_mfma_f32_16x16x32_bf16 v[102:105], v[86:89], v[206:209], v[102:105]
	s_setprio 0
	s_barrier
	s_add_i32 s0, s0, s61
	v_lshl_add_u64 v[210:211], v[210:211], 0, s[76:77]
	s_mov_b32 m0, s0
	ds_read_b128 v[162:165], v239 offset:49152
	ds_read_b128 v[166:169], v239 offset:50176
	ds_read_b128 v[170:173], v239 offset:51200
	ds_read_b128 v[174:177], v239 offset:52224
	ds_read_b128 v[178:181], v239 offset:53248
	ds_read_b128 v[198:201], v239 offset:54272
	ds_read_b128 v[202:205], v239 offset:55296
	ds_read_b128 v[206:209], v239 offset:56320
	global_load_lds_dwordx4 v[210:211], off
	v_lshl_add_u64 v[210:211], v[212:213], 0, s[76:77]
	s_add_i32 m0, s0, 0x2000
	s_add_i32 s0, s27, s61
	global_load_lds_dwordx4 v[210:211], off
	v_lshl_add_u64 v[210:211], v[214:215], 0, s[76:77]
	s_mov_b32 m0, s0
	s_nop 0
	global_load_lds_dwordx4 v[210:211], off
	v_lshl_add_u64 v[210:211], v[216:217], 0, s[76:77]
	s_add_i32 m0, s0, 0x2000
	s_nop 0
	global_load_lds_dwordx4 v[210:211], off
	v_lshl_add_u64 v[210:211], v[218:219], 0, s[76:77]
	s_mov_b32 m0, s68
	s_nop 0
	global_load_lds_dwordx4 v[210:211], off
	v_lshl_add_u64 v[210:211], v[230:231], 0, s[76:77]
	s_mov_b32 m0, s69
	s_nop 0
	global_load_lds_dwordx4 v[210:211], off
	s_waitcnt vmcnt(8)
	s_waitcnt lgkmcnt(0)
	s_barrier
	s_setprio 1
	s_waitcnt lgkmcnt(0)
	v_mfma_f32_16x16x32_bf16 v[78:81], v[58:61], v[162:165], v[78:81]
	v_mfma_f32_16x16x32_bf16 v[74:77], v[66:69], v[162:165], v[74:77]
	v_mfma_f32_16x16x32_bf16 v[42:45], v[66:69], v[170:173], v[42:45]
	v_mfma_f32_16x16x32_bf16 v[46:49], v[58:61], v[170:173], v[46:49]
	v_mfma_f32_16x16x32_bf16 v[30:33], v[58:61], v[178:181], v[30:33]
	v_mfma_f32_16x16x32_bf16 v[26:29], v[66:69], v[178:181], v[26:29]
	v_mfma_f32_16x16x32_bf16 v[10:13], v[66:69], v[202:205], v[10:13]
	v_mfma_f32_16x16x32_bf16 v[14:17], v[58:61], v[202:205], v[14:17]
	v_mfma_f32_16x16x32_bf16 v[78:81], v[62:65], v[166:169], v[78:81]
	v_mfma_f32_16x16x32_bf16 v[74:77], v[70:73], v[166:169], v[74:77]
	v_mfma_f32_16x16x32_bf16 v[42:45], v[70:73], v[174:177], v[42:45]
	v_mfma_f32_16x16x32_bf16 v[46:49], v[62:65], v[174:177], v[46:49]
	v_mfma_f32_16x16x32_bf16 v[30:33], v[62:65], v[198:201], v[30:33]
	v_mfma_f32_16x16x32_bf16 v[26:29], v[70:73], v[198:201], v[26:29]
	v_mfma_f32_16x16x32_bf16 v[10:13], v[70:73], v[206:209], v[10:13]
	v_mfma_f32_16x16x32_bf16 v[14:17], v[62:65], v[206:209], v[14:17]
	s_setprio 0
	s_setprio 1
	v_mfma_f32_16x16x32_bf16 v[54:57], v[82:85], v[162:165], v[54:57]
	v_mfma_f32_16x16x32_bf16 v[50:53], v[90:93], v[162:165], v[50:53]
	v_mfma_f32_16x16x32_bf16 v[34:37], v[90:93], v[170:173], v[34:37]
	v_mfma_f32_16x16x32_bf16 v[38:41], v[82:85], v[170:173], v[38:41]
	v_mfma_f32_16x16x32_bf16 v[22:25], v[82:85], v[178:181], v[22:25]
	v_mfma_f32_16x16x32_bf16 v[18:21], v[90:93], v[178:181], v[18:21]
	v_mfma_f32_16x16x32_bf16 v[2:5], v[90:93], v[202:205], v[2:5]
	v_mfma_f32_16x16x32_bf16 v[6:9], v[82:85], v[202:205], v[6:9]
	v_mfma_f32_16x16x32_bf16 v[54:57], v[86:89], v[166:169], v[54:57]
	v_mfma_f32_16x16x32_bf16 v[50:53], v[94:97], v[166:169], v[50:53]
	v_mfma_f32_16x16x32_bf16 v[34:37], v[94:97], v[174:177], v[34:37]
	v_mfma_f32_16x16x32_bf16 v[38:41], v[86:89], v[174:177], v[38:41]
	v_mfma_f32_16x16x32_bf16 v[22:25], v[86:89], v[198:201], v[22:25]
	v_mfma_f32_16x16x32_bf16 v[18:21], v[94:97], v[198:201], v[18:21]
	v_mfma_f32_16x16x32_bf16 v[2:5], v[94:97], v[206:209], v[2:5]
	v_mfma_f32_16x16x32_bf16 v[6:9], v[86:89], v[206:209], v[6:9]
	s_setprio 0
	s_barrier
	s_add_u32 s6, s6, 0x100
	s_addc_u32 s7, s7, 0
	s_add_u32 s21, s21, 0x100
	s_addc_u32 s26, s26, 0
	s_mov_b32 s27, s46
.LBB0_671:
	s_add_i32 s46, s27, 2
	s_add_u32 s0, s6, 0x80
	s_addc_u32 s56, s7, 0
	s_add_i32 vcc_lo, 0, 0x10000
	s_cmp_eq_u32 s72, s27
	s_cselect_b32 s57, s51, s56
	s_cselect_b32 s56, s50, s0
	s_cselect_b32 s59, s53, s26
	s_cselect_b32 s58, s52, s21
	s_add_i32 s0, 0, 0x14000
	v_add_u32_e32 v70, vcc_lo, v237
	v_add_u32_e32 v94, s0, v237
	ds_read_b128 v[58:61], v70
	ds_read_b128 v[62:65], v70 offset:1024
	ds_read_b128 v[66:69], v70 offset:2048
	ds_read_b128 v[70:73], v70 offset:3072
	ds_read_b128 v[82:85], v94
	ds_read_b128 v[86:89], v94 offset:1024
	ds_read_b128 v[90:93], v94 offset:2048
	ds_read_b128 v[94:97], v94 offset:3072
	v_lshl_add_u64 v[210:211], s[6:7], 0, v[194:195]
	s_add_i32 m0, s64, 0xc000
	ds_read_b128 v[162:165], v239
	ds_read_b128 v[166:169], v239 offset:1024
	ds_read_b128 v[170:173], v239 offset:2048
	ds_read_b128 v[174:177], v239 offset:3072
	ds_read_b128 v[178:181], v239 offset:4096
	ds_read_b128 v[198:201], v239 offset:5120
	ds_read_b128 v[202:205], v239 offset:6144
	ds_read_b128 v[206:209], v239 offset:7168
	global_load_lds_dwordx4 v[210:211], off
	v_lshl_add_u64 v[210:211], s[6:7], 0, v[196:197]
	s_add_i32 m0, s64, 0xe000
	s_nop 0
	global_load_lds_dwordx4 v[210:211], off
	s_waitcnt vmcnt(8)
	s_waitcnt lgkmcnt(0)
	s_barrier
	s_setprio 1
	s_waitcnt lgkmcnt(0)
	v_mfma_f32_16x16x32_bf16 v[158:161], v[58:61], v[162:165], v[158:161]
	v_mfma_f32_16x16x32_bf16 v[154:157], v[66:69], v[162:165], v[154:157]
	v_mfma_f32_16x16x32_bf16 v[138:141], v[66:69], v[170:173], v[138:141]
	v_mfma_f32_16x16x32_bf16 v[142:145], v[58:61], v[170:173], v[142:145]
	v_mfma_f32_16x16x32_bf16 v[126:129], v[58:61], v[178:181], v[126:129]
	v_mfma_f32_16x16x32_bf16 v[122:125], v[66:69], v[178:181], v[122:125]
	v_mfma_f32_16x16x32_bf16 v[106:109], v[66:69], v[202:205], v[106:109]
	v_mfma_f32_16x16x32_bf16 v[110:113], v[58:61], v[202:205], v[110:113]
	v_mfma_f32_16x16x32_bf16 v[158:161], v[62:65], v[166:169], v[158:161]
	v_mfma_f32_16x16x32_bf16 v[154:157], v[70:73], v[166:169], v[154:157]
	v_mfma_f32_16x16x32_bf16 v[138:141], v[70:73], v[174:177], v[138:141]
	v_mfma_f32_16x16x32_bf16 v[142:145], v[62:65], v[174:177], v[142:145]
	v_mfma_f32_16x16x32_bf16 v[126:129], v[62:65], v[198:201], v[126:129]
	v_mfma_f32_16x16x32_bf16 v[122:125], v[70:73], v[198:201], v[122:125]
	v_mfma_f32_16x16x32_bf16 v[106:109], v[70:73], v[206:209], v[106:109]
	v_mfma_f32_16x16x32_bf16 v[110:113], v[62:65], v[206:209], v[110:113]
	s_setprio 0
	s_setprio 1
	v_mfma_f32_16x16x32_bf16 v[150:153], v[82:85], v[162:165], v[150:153]
	v_mfma_f32_16x16x32_bf16 v[146:149], v[90:93], v[162:165], v[146:149]
	v_mfma_f32_16x16x32_bf16 v[130:133], v[90:93], v[170:173], v[130:133]
	v_mfma_f32_16x16x32_bf16 v[134:137], v[82:85], v[170:173], v[134:137]
	v_mfma_f32_16x16x32_bf16 v[118:121], v[82:85], v[178:181], v[118:121]
	v_mfma_f32_16x16x32_bf16 v[114:117], v[90:93], v[178:181], v[114:117]
	v_mfma_f32_16x16x32_bf16 v[98:101], v[90:93], v[202:205], v[98:101]
	v_mfma_f32_16x16x32_bf16 v[102:105], v[82:85], v[202:205], v[102:105]
	v_mfma_f32_16x16x32_bf16 v[150:153], v[86:89], v[166:169], v[150:153]
	v_mfma_f32_16x16x32_bf16 v[146:149], v[94:97], v[166:169], v[146:149]
	v_mfma_f32_16x16x32_bf16 v[130:133], v[94:97], v[174:177], v[130:133]
	v_mfma_f32_16x16x32_bf16 v[134:137], v[86:89], v[174:177], v[134:137]
	v_mfma_f32_16x16x32_bf16 v[118:121], v[86:89], v[198:201], v[118:121]
	v_mfma_f32_16x16x32_bf16 v[114:117], v[94:97], v[198:201], v[114:117]
	v_mfma_f32_16x16x32_bf16 v[98:101], v[94:97], v[206:209], v[98:101]
	v_mfma_f32_16x16x32_bf16 v[102:105], v[86:89], v[206:209], v[102:105]
	s_setprio 0
	s_barrier
	s_add_i32 s27, vcc_lo, s61
	v_lshl_add_u64 v[210:211], s[58:59], 0, v[186:187]
	s_mov_b32 m0, s27
	ds_read_b128 v[162:165], v239 offset:16384
	ds_read_b128 v[166:169], v239 offset:17408
	ds_read_b128 v[170:173], v239 offset:18432
	ds_read_b128 v[174:177], v239 offset:19456
	ds_read_b128 v[178:181], v239 offset:20480
	ds_read_b128 v[198:201], v239 offset:21504
	ds_read_b128 v[202:205], v239 offset:22528
	ds_read_b128 v[206:209], v239 offset:23552
	global_load_lds_dwordx4 v[210:211], off
	s_add_i32 m0, s27, 0x2000
	v_lshl_add_u64 v[212:213], s[58:59], 0, v[182:183]
	s_add_u32 s58, s58, s12
	s_addc_u32 s59, s59, 0
	s_add_i32 s0, s0, s61
	global_load_lds_dwordx4 v[212:213], off
	v_lshl_add_u64 v[214:215], s[58:59], 0, v[186:187]
	s_mov_b32 m0, s0
	v_lshl_add_u64 v[216:217], s[58:59], 0, v[182:183]
	global_load_lds_dwordx4 v[214:215], off
	s_add_i32 m0, s0, 0x2000
	v_lshl_add_u64 v[218:219], s[56:57], 0, v[188:189]
	global_load_lds_dwordx4 v[216:217], off
	s_mov_b32 m0, s64
	v_lshl_add_u64 v[230:231], s[56:57], 0, v[184:185]
	global_load_lds_dwordx4 v[218:219], off
	s_mov_b32 m0, s65
	s_nop 0
	global_load_lds_dwordx4 v[230:231], off
	s_waitcnt vmcnt(8)
	s_waitcnt lgkmcnt(0)
	s_barrier
	s_setprio 1
	s_waitcnt lgkmcnt(0)
	v_mfma_f32_16x16x32_bf16 v[78:81], v[58:61], v[162:165], v[78:81]
	v_mfma_f32_16x16x32_bf16 v[74:77], v[66:69], v[162:165], v[74:77]
	v_mfma_f32_16x16x32_bf16 v[42:45], v[66:69], v[170:173], v[42:45]
	v_mfma_f32_16x16x32_bf16 v[46:49], v[58:61], v[170:173], v[46:49]
	v_mfma_f32_16x16x32_bf16 v[30:33], v[58:61], v[178:181], v[30:33]
	v_mfma_f32_16x16x32_bf16 v[26:29], v[66:69], v[178:181], v[26:29]
	v_mfma_f32_16x16x32_bf16 v[10:13], v[66:69], v[202:205], v[10:13]
	v_mfma_f32_16x16x32_bf16 v[14:17], v[58:61], v[202:205], v[14:17]
	v_mfma_f32_16x16x32_bf16 v[78:81], v[62:65], v[166:169], v[78:81]
	v_mfma_f32_16x16x32_bf16 v[74:77], v[70:73], v[166:169], v[74:77]
	v_mfma_f32_16x16x32_bf16 v[42:45], v[70:73], v[174:177], v[42:45]
	v_mfma_f32_16x16x32_bf16 v[46:49], v[62:65], v[174:177], v[46:49]
	v_mfma_f32_16x16x32_bf16 v[30:33], v[62:65], v[198:201], v[30:33]
	v_mfma_f32_16x16x32_bf16 v[26:29], v[70:73], v[198:201], v[26:29]
	v_mfma_f32_16x16x32_bf16 v[10:13], v[70:73], v[206:209], v[10:13]
	v_mfma_f32_16x16x32_bf16 v[14:17], v[62:65], v[206:209], v[14:17]
	s_setprio 0
	s_setprio 1
	v_mfma_f32_16x16x32_bf16 v[54:57], v[82:85], v[162:165], v[54:57]
	v_mfma_f32_16x16x32_bf16 v[50:53], v[90:93], v[162:165], v[50:53]
	v_mfma_f32_16x16x32_bf16 v[34:37], v[90:93], v[170:173], v[34:37]
	v_mfma_f32_16x16x32_bf16 v[38:41], v[82:85], v[170:173], v[38:41]
	v_mfma_f32_16x16x32_bf16 v[22:25], v[82:85], v[178:181], v[22:25]
	v_mfma_f32_16x16x32_bf16 v[18:21], v[90:93], v[178:181], v[18:21]
	v_mfma_f32_16x16x32_bf16 v[2:5], v[90:93], v[202:205], v[2:5]
	v_mfma_f32_16x16x32_bf16 v[6:9], v[82:85], v[202:205], v[6:9]
	v_mfma_f32_16x16x32_bf16 v[54:57], v[86:89], v[166:169], v[54:57]
	v_mfma_f32_16x16x32_bf16 v[50:53], v[94:97], v[166:169], v[50:53]
	v_mfma_f32_16x16x32_bf16 v[34:37], v[94:97], v[174:177], v[34:37]
	v_mfma_f32_16x16x32_bf16 v[38:41], v[86:89], v[174:177], v[38:41]
	v_mfma_f32_16x16x32_bf16 v[22:25], v[86:89], v[198:201], v[22:25]
	v_mfma_f32_16x16x32_bf16 v[18:21], v[94:97], v[198:201], v[18:21]
	v_mfma_f32_16x16x32_bf16 v[2:5], v[94:97], v[206:209], v[2:5]
	v_mfma_f32_16x16x32_bf16 v[6:9], v[86:89], v[206:209], v[6:9]
	s_setprio 0
	s_barrier
	s_add_i32 s0, 0, 0x18000
	s_add_i32 s27, 0, 0x1c000
	v_add_u32_e32 v70, s0, v237
	v_add_u32_e32 v94, s27, v237
	ds_read_b128 v[58:61], v70
	ds_read_b128 v[62:65], v70 offset:1024
	ds_read_b128 v[66:69], v70 offset:2048
	ds_read_b128 v[70:73], v70 offset:3072
	ds_read_b128 v[82:85], v94
	ds_read_b128 v[86:89], v94 offset:1024
	ds_read_b128 v[90:93], v94 offset:2048
	ds_read_b128 v[94:97], v94 offset:3072
	s_add_u32 s56, s56, s12
	s_addc_u32 s57, s57, 0
	s_mov_b32 m0, s66
	v_lshl_add_u64 v[232:233], s[56:57], 0, v[188:189]
	ds_read_b128 v[162:165], v239 offset:32768
	ds_read_b128 v[166:169], v239 offset:33792
	ds_read_b128 v[170:173], v239 offset:34816
	ds_read_b128 v[174:177], v239 offset:35840
	ds_read_b128 v[178:181], v239 offset:36864
	ds_read_b128 v[198:201], v239 offset:37888
	ds_read_b128 v[202:205], v239 offset:38912
	ds_read_b128 v[206:209], v239 offset:39936
	global_load_lds_dwordx4 v[232:233], off
	v_lshl_add_u64 v[232:233], s[56:57], 0, v[184:185]
	s_mov_b32 m0, s67
	s_nop 0
	global_load_lds_dwordx4 v[232:233], off
	s_waitcnt vmcnt(8)
	s_waitcnt lgkmcnt(0)
	s_barrier
	s_setprio 1
	s_waitcnt lgkmcnt(0)
	v_mfma_f32_16x16x32_bf16 v[158:161], v[58:61], v[162:165], v[158:161]
	v_mfma_f32_16x16x32_bf16 v[154:157], v[66:69], v[162:165], v[154:157]
	v_mfma_f32_16x16x32_bf16 v[138:141], v[66:69], v[170:173], v[138:141]
	v_mfma_f32_16x16x32_bf16 v[142:145], v[58:61], v[170:173], v[142:145]
	v_mfma_f32_16x16x32_bf16 v[126:129], v[58:61], v[178:181], v[126:129]
	v_mfma_f32_16x16x32_bf16 v[122:125], v[66:69], v[178:181], v[122:125]
	v_mfma_f32_16x16x32_bf16 v[106:109], v[66:69], v[202:205], v[106:109]
	v_mfma_f32_16x16x32_bf16 v[110:113], v[58:61], v[202:205], v[110:113]
	v_mfma_f32_16x16x32_bf16 v[158:161], v[62:65], v[166:169], v[158:161]
	v_mfma_f32_16x16x32_bf16 v[154:157], v[70:73], v[166:169], v[154:157]
	v_mfma_f32_16x16x32_bf16 v[138:141], v[70:73], v[174:177], v[138:141]
	v_mfma_f32_16x16x32_bf16 v[142:145], v[62:65], v[174:177], v[142:145]
	v_mfma_f32_16x16x32_bf16 v[126:129], v[62:65], v[198:201], v[126:129]
	v_mfma_f32_16x16x32_bf16 v[122:125], v[70:73], v[198:201], v[122:125]
	v_mfma_f32_16x16x32_bf16 v[106:109], v[70:73], v[206:209], v[106:109]
	v_mfma_f32_16x16x32_bf16 v[110:113], v[62:65], v[206:209], v[110:113]
	s_setprio 0
	s_setprio 1
	v_mfma_f32_16x16x32_bf16 v[150:153], v[82:85], v[162:165], v[150:153]
	v_mfma_f32_16x16x32_bf16 v[146:149], v[90:93], v[162:165], v[146:149]
	v_mfma_f32_16x16x32_bf16 v[130:133], v[90:93], v[170:173], v[130:133]
	v_mfma_f32_16x16x32_bf16 v[134:137], v[82:85], v[170:173], v[134:137]
	v_mfma_f32_16x16x32_bf16 v[118:121], v[82:85], v[178:181], v[118:121]
	v_mfma_f32_16x16x32_bf16 v[114:117], v[90:93], v[178:181], v[114:117]
	v_mfma_f32_16x16x32_bf16 v[98:101], v[90:93], v[202:205], v[98:101]
	v_mfma_f32_16x16x32_bf16 v[102:105], v[82:85], v[202:205], v[102:105]
	v_mfma_f32_16x16x32_bf16 v[150:153], v[86:89], v[166:169], v[150:153]
	v_mfma_f32_16x16x32_bf16 v[146:149], v[94:97], v[166:169], v[146:149]
	v_mfma_f32_16x16x32_bf16 v[130:133], v[94:97], v[174:177], v[130:133]
	v_mfma_f32_16x16x32_bf16 v[134:137], v[86:89], v[174:177], v[134:137]
	v_mfma_f32_16x16x32_bf16 v[118:121], v[86:89], v[198:201], v[118:121]
	v_mfma_f32_16x16x32_bf16 v[114:117], v[94:97], v[198:201], v[114:117]
	v_mfma_f32_16x16x32_bf16 v[98:101], v[94:97], v[206:209], v[98:101]
	v_mfma_f32_16x16x32_bf16 v[102:105], v[86:89], v[206:209], v[102:105]
	s_setprio 0
	s_barrier
	s_add_i32 s0, s0, s61
	v_lshl_add_u64 v[210:211], v[210:211], 0, s[76:77]
	s_mov_b32 m0, s0
	ds_read_b128 v[162:165], v239 offset:49152
	ds_read_b128 v[166:169], v239 offset:50176
	ds_read_b128 v[170:173], v239 offset:51200
	ds_read_b128 v[174:177], v239 offset:52224
	ds_read_b128 v[178:181], v239 offset:53248
	ds_read_b128 v[198:201], v239 offset:54272
	ds_read_b128 v[202:205], v239 offset:55296
	ds_read_b128 v[206:209], v239 offset:56320
	global_load_lds_dwordx4 v[210:211], off
	v_lshl_add_u64 v[210:211], v[212:213], 0, s[76:77]
	s_add_i32 m0, s0, 0x2000
	s_add_i32 s0, s27, s61
	global_load_lds_dwordx4 v[210:211], off
	v_lshl_add_u64 v[210:211], v[214:215], 0, s[76:77]
	s_mov_b32 m0, s0
	s_nop 0
	global_load_lds_dwordx4 v[210:211], off
	v_lshl_add_u64 v[210:211], v[216:217], 0, s[76:77]
	s_add_i32 m0, s0, 0x2000
	s_nop 0
	global_load_lds_dwordx4 v[210:211], off
	v_lshl_add_u64 v[210:211], v[218:219], 0, s[76:77]
	s_mov_b32 m0, s68
	s_nop 0
	global_load_lds_dwordx4 v[210:211], off
	v_lshl_add_u64 v[210:211], v[230:231], 0, s[76:77]
	s_mov_b32 m0, s69
	s_nop 0
	global_load_lds_dwordx4 v[210:211], off
	s_waitcnt vmcnt(8)
	s_waitcnt lgkmcnt(0)
	s_barrier
	s_setprio 1
	s_waitcnt lgkmcnt(0)
	v_mfma_f32_16x16x32_bf16 v[78:81], v[58:61], v[162:165], v[78:81]
	v_mfma_f32_16x16x32_bf16 v[74:77], v[66:69], v[162:165], v[74:77]
	v_mfma_f32_16x16x32_bf16 v[42:45], v[66:69], v[170:173], v[42:45]
	v_mfma_f32_16x16x32_bf16 v[46:49], v[58:61], v[170:173], v[46:49]
	v_mfma_f32_16x16x32_bf16 v[30:33], v[58:61], v[178:181], v[30:33]
	v_mfma_f32_16x16x32_bf16 v[26:29], v[66:69], v[178:181], v[26:29]
	v_mfma_f32_16x16x32_bf16 v[10:13], v[66:69], v[202:205], v[10:13]
	v_mfma_f32_16x16x32_bf16 v[14:17], v[58:61], v[202:205], v[14:17]
	v_mfma_f32_16x16x32_bf16 v[78:81], v[62:65], v[166:169], v[78:81]
	v_mfma_f32_16x16x32_bf16 v[74:77], v[70:73], v[166:169], v[74:77]
	v_mfma_f32_16x16x32_bf16 v[42:45], v[70:73], v[174:177], v[42:45]
	v_mfma_f32_16x16x32_bf16 v[46:49], v[62:65], v[174:177], v[46:49]
	v_mfma_f32_16x16x32_bf16 v[30:33], v[62:65], v[198:201], v[30:33]
	v_mfma_f32_16x16x32_bf16 v[26:29], v[70:73], v[198:201], v[26:29]
	v_mfma_f32_16x16x32_bf16 v[10:13], v[70:73], v[206:209], v[10:13]
	v_mfma_f32_16x16x32_bf16 v[14:17], v[62:65], v[206:209], v[14:17]
	s_setprio 0
	s_setprio 1
	v_mfma_f32_16x16x32_bf16 v[54:57], v[82:85], v[162:165], v[54:57]
	v_mfma_f32_16x16x32_bf16 v[50:53], v[90:93], v[162:165], v[50:53]
	v_mfma_f32_16x16x32_bf16 v[34:37], v[90:93], v[170:173], v[34:37]
	v_mfma_f32_16x16x32_bf16 v[38:41], v[82:85], v[170:173], v[38:41]
	v_mfma_f32_16x16x32_bf16 v[22:25], v[82:85], v[178:181], v[22:25]
	v_mfma_f32_16x16x32_bf16 v[18:21], v[90:93], v[178:181], v[18:21]
	v_mfma_f32_16x16x32_bf16 v[2:5], v[90:93], v[202:205], v[2:5]
	v_mfma_f32_16x16x32_bf16 v[6:9], v[82:85], v[202:205], v[6:9]
	v_mfma_f32_16x16x32_bf16 v[54:57], v[86:89], v[166:169], v[54:57]
	v_mfma_f32_16x16x32_bf16 v[50:53], v[94:97], v[166:169], v[50:53]
	v_mfma_f32_16x16x32_bf16 v[34:37], v[94:97], v[174:177], v[34:37]
	v_mfma_f32_16x16x32_bf16 v[38:41], v[86:89], v[174:177], v[38:41]
	v_mfma_f32_16x16x32_bf16 v[22:25], v[86:89], v[198:201], v[22:25]
	v_mfma_f32_16x16x32_bf16 v[18:21], v[94:97], v[198:201], v[18:21]
	v_mfma_f32_16x16x32_bf16 v[2:5], v[94:97], v[206:209], v[2:5]
	v_mfma_f32_16x16x32_bf16 v[6:9], v[86:89], v[206:209], v[6:9]
	s_setprio 0
	s_barrier
	s_add_u32 s6, s6, 0x100
	s_addc_u32 s7, s7, 0
	s_add_u32 s21, s21, 0x100
	s_addc_u32 s26, s26, 0
	s_cmp_ge_u32 s46, s36
	s_mov_b32 s27, s46
	s_cbranch_scc0 .LBB0_671
	s_and_b64 vcc, exec, s[30:31]
	s_cbranch_vccz .LBB0_674
	s_barrier
